# GEMM main loops: removed the redundant back-to-back s_setprio 0 / s_setprio 1 pairs in the middle of each 32-MFMA block (32 sites)
# baseline (speedup 1.0000x reference)
.LBB0_183:
	s_add_u32 s12, s42, 0xfffc0080
	s_addc_u32 s13, s43, -1
	s_add_i32 s15, 0, 0x10000
	s_cmp_eq_u32 vcc_lo, 12
	s_cselect_b32 s49, s11, s13
	s_cselect_b32 s48, s27, s12
	v_add_u32_e32 v0, s15, v188
	s_cselect_b32 s47, s25, s90
	s_cselect_b32 s46, s35, s85
	s_add_i32 s50, 0, 0x14000
	ds_read_b128 v[42:45], v0
	ds_read_b128 v[54:57], v0 offset:1024
	ds_read_b128 v[58:61], v0 offset:2048
	ds_read_b128 v[70:73], v0 offset:3072
	v_add_u32_e32 v0, s50, v188
	ds_read_b128 v[184:187], v0
	ds_read_b128 v[202:205], v0 offset:1024
	ds_read_b128 v[206:209], v0 offset:2048
	ds_read_b128 v[210:213], v0 offset:3072
	v_lshl_add_u64 v[200:201], s[42:43], 0, v[182:183]
	s_add_i32 m0, s92, 0xc000
	ds_read_b128 v[214:217], v192
	ds_read_b128 v[218:221], v192 offset:1024
	ds_read_b128 v[222:225], v192 offset:2048
	ds_read_b128 v[226:229], v192 offset:3072
	ds_read_b128 v[230:233], v192 offset:4096
	ds_read_b128 v[234:237], v192 offset:5120
	ds_read_b128 v[238:241], v192 offset:6144
	ds_read_b128 v[242:245], v192 offset:7168
	global_load_lds_dwordx4 v[200:201], off
	v_lshl_add_u64 v[200:201], s[42:43], 0, v[156:157]
	s_add_i32 m0, s92, 0xe000
	s_nop 0
	global_load_lds_dwordx4 v[200:201], off
	s_waitcnt vmcnt(8)
	s_waitcnt lgkmcnt(0)
	s_barrier
	s_setprio 1
	s_waitcnt lgkmcnt(0)
	v_mfma_f32_16x16x32_bf16 v[142:145], v[42:45], v[214:217], v[142:145]
	v_mfma_f32_16x16x32_bf16 v[138:141], v[58:61], v[214:217], v[138:141]
	v_mfma_f32_16x16x32_bf16 v[126:129], v[42:45], v[222:225], v[126:129]
	v_mfma_f32_16x16x32_bf16 v[122:125], v[58:61], v[222:225], v[122:125]
	v_mfma_f32_16x16x32_bf16 v[110:113], v[42:45], v[230:233], v[110:113]
	v_mfma_f32_16x16x32_bf16 v[106:109], v[58:61], v[230:233], v[106:109]
	v_mfma_f32_16x16x32_bf16 v[94:97], v[42:45], v[238:241], v[94:97]
	v_mfma_f32_16x16x32_bf16 v[90:93], v[58:61], v[238:241], v[90:93]
	v_mfma_f32_16x16x32_bf16 v[142:145], v[54:57], v[218:221], v[142:145]
	v_mfma_f32_16x16x32_bf16 v[138:141], v[70:73], v[218:221], v[138:141]
	v_mfma_f32_16x16x32_bf16 v[126:129], v[54:57], v[226:229], v[126:129]
	v_mfma_f32_16x16x32_bf16 v[122:125], v[70:73], v[226:229], v[122:125]
	v_mfma_f32_16x16x32_bf16 v[110:113], v[54:57], v[234:237], v[110:113]
	v_mfma_f32_16x16x32_bf16 v[106:109], v[70:73], v[234:237], v[106:109]
	v_mfma_f32_16x16x32_bf16 v[94:97], v[54:57], v[242:245], v[94:97]
	v_mfma_f32_16x16x32_bf16 v[90:93], v[70:73], v[242:245], v[90:93]
	v_mfma_f32_16x16x32_bf16 v[134:137], v[184:187], v[214:217], v[134:137]
	v_mfma_f32_16x16x32_bf16 v[130:133], v[206:209], v[214:217], v[130:133]
	v_mfma_f32_16x16x32_bf16 v[118:121], v[184:187], v[222:225], v[118:121]
	v_mfma_f32_16x16x32_bf16 v[114:117], v[206:209], v[222:225], v[114:117]
	v_mfma_f32_16x16x32_bf16 v[102:105], v[184:187], v[230:233], v[102:105]
	v_mfma_f32_16x16x32_bf16 v[98:101], v[206:209], v[230:233], v[98:101]
	v_mfma_f32_16x16x32_bf16 v[86:89], v[184:187], v[238:241], v[86:89]
	v_mfma_f32_16x16x32_bf16 v[82:85], v[206:209], v[238:241], v[82:85]
	v_mfma_f32_16x16x32_bf16 v[134:137], v[202:205], v[218:221], v[134:137]
	v_mfma_f32_16x16x32_bf16 v[130:133], v[210:213], v[218:221], v[130:133]
	v_mfma_f32_16x16x32_bf16 v[118:121], v[202:205], v[226:229], v[118:121]
	v_mfma_f32_16x16x32_bf16 v[114:117], v[210:213], v[226:229], v[114:117]
	v_mfma_f32_16x16x32_bf16 v[102:105], v[202:205], v[234:237], v[102:105]
	v_mfma_f32_16x16x32_bf16 v[98:101], v[210:213], v[234:237], v[98:101]
	v_mfma_f32_16x16x32_bf16 v[86:89], v[202:205], v[242:245], v[86:89]
	v_mfma_f32_16x16x32_bf16 v[82:85], v[210:213], v[242:245], v[82:85]
	s_setprio 0
	s_barrier
	s_add_i32 s12, s15, s81
	v_lshl_add_u64 v[200:201], s[46:47], 0, v[148:149]
	s_mov_b32 m0, s12
	ds_read_b128 v[214:217], v192 offset:16384
	ds_read_b128 v[218:221], v192 offset:17408
	ds_read_b128 v[222:225], v192 offset:18432
	ds_read_b128 v[226:229], v192 offset:19456
	ds_read_b128 v[230:233], v192 offset:20480
	ds_read_b128 v[234:237], v192 offset:21504
	ds_read_b128 v[238:241], v192 offset:22528
	ds_read_b128 v[242:245], v192 offset:23552
	global_load_lds_dwordx4 v[200:201], off
	s_add_i32 m0, s12, 0x2000
	s_add_u32 s12, s46, 0x40000
	v_lshl_add_u64 v[246:247], s[46:47], 0, v[152:153]
	s_addc_u32 s13, s47, 0
	s_add_i32 s15, s50, s81
	global_load_lds_dwordx4 v[246:247], off
	v_lshl_add_u64 v[248:249], s[12:13], 0, v[148:149]
	s_mov_b32 m0, s15
	v_lshl_add_u64 v[250:251], s[48:49], 0, v[150:151]
	global_load_lds_dwordx4 v[248:249], off
	v_lshl_add_u64 v[248:249], s[12:13], 0, v[152:153]
	s_add_i32 m0, s15, 0x2000
	s_nop 0
	global_load_lds_dwordx4 v[248:249], off
	v_lshl_add_u64 v[248:249], s[48:49], 0, v[146:147]
	s_mov_b32 m0, s92
	s_nop 0
	global_load_lds_dwordx4 v[248:249], off
	s_mov_b32 m0, s93
	s_nop 0
	global_load_lds_dwordx4 v[250:251], off
	s_waitcnt vmcnt(8)
	s_waitcnt lgkmcnt(0)
	s_barrier
	s_setprio 1
	s_waitcnt lgkmcnt(0)
	v_mfma_f32_16x16x32_bf16 v[78:81], v[42:45], v[214:217], v[78:81]
	v_mfma_f32_16x16x32_bf16 v[74:77], v[58:61], v[214:217], v[74:77]
	v_mfma_f32_16x16x32_bf16 v[50:53], v[42:45], v[222:225], v[50:53]
	v_mfma_f32_16x16x32_bf16 v[46:49], v[58:61], v[222:225], v[46:49]
	v_mfma_f32_16x16x32_bf16 v[30:33], v[42:45], v[230:233], v[30:33]
	v_mfma_f32_16x16x32_bf16 v[26:29], v[58:61], v[230:233], v[26:29]
	v_mfma_f32_16x16x32_bf16 v[14:17], v[42:45], v[238:241], v[14:17]
	v_mfma_f32_16x16x32_bf16 v[10:13], v[58:61], v[238:241], v[10:13]
	v_mfma_f32_16x16x32_bf16 v[78:81], v[54:57], v[218:221], v[78:81]
	v_mfma_f32_16x16x32_bf16 v[74:77], v[70:73], v[218:221], v[74:77]
	v_mfma_f32_16x16x32_bf16 v[50:53], v[54:57], v[226:229], v[50:53]
	v_mfma_f32_16x16x32_bf16 v[46:49], v[70:73], v[226:229], v[46:49]
	v_mfma_f32_16x16x32_bf16 v[30:33], v[54:57], v[234:237], v[30:33]
	v_mfma_f32_16x16x32_bf16 v[26:29], v[70:73], v[234:237], v[26:29]
	v_mfma_f32_16x16x32_bf16 v[14:17], v[54:57], v[242:245], v[14:17]
	v_mfma_f32_16x16x32_bf16 v[10:13], v[70:73], v[242:245], v[10:13]
	v_mfma_f32_16x16x32_bf16 v[38:41], v[184:187], v[222:225], v[38:41]
	v_mfma_f32_16x16x32_bf16 v[34:37], v[206:209], v[222:225], v[34:37]
	v_mfma_f32_16x16x32_bf16 v[22:25], v[184:187], v[230:233], v[22:25]
	v_mfma_f32_16x16x32_bf16 v[18:21], v[206:209], v[230:233], v[18:21]
	v_mfma_f32_16x16x32_bf16 v[6:9], v[184:187], v[238:241], v[6:9]
	v_mfma_f32_16x16x32_bf16 v[2:5], v[206:209], v[238:241], v[2:5]
	v_mfma_f32_16x16x32_bf16 v[42:45], v[184:187], v[214:217], v[66:69]
	v_mfma_f32_16x16x32_bf16 v[54:57], v[206:209], v[214:217], v[62:65]
	v_mfma_f32_16x16x32_bf16 v[38:41], v[202:205], v[226:229], v[38:41]
	v_mfma_f32_16x16x32_bf16 v[34:37], v[210:213], v[226:229], v[34:37]
	v_mfma_f32_16x16x32_bf16 v[22:25], v[202:205], v[234:237], v[22:25]
	v_mfma_f32_16x16x32_bf16 v[18:21], v[210:213], v[234:237], v[18:21]
	v_mfma_f32_16x16x32_bf16 v[6:9], v[202:205], v[242:245], v[6:9]
	v_mfma_f32_16x16x32_bf16 v[2:5], v[210:213], v[242:245], v[2:5]
	v_mfma_f32_16x16x32_bf16 v[42:45], v[202:205], v[218:221], v[42:45]
	v_mfma_f32_16x16x32_bf16 v[54:57], v[210:213], v[218:221], v[54:57]
	s_setprio 0
	s_barrier
	s_add_i32 s15, 0, 0x18000
	v_add_u32_e32 v0, s15, v188
	s_add_i32 s50, 0, 0x1c000
	ds_read_b128 v[58:61], v0
	ds_read_b128 v[62:65], v0 offset:1024
	ds_read_b128 v[66:69], v0 offset:2048
	ds_read_b128 v[70:73], v0 offset:3072
	v_add_u32_e32 v0, s50, v188
	ds_read_b128 v[184:187], v0
	ds_read_b128 v[202:205], v0 offset:1024
	ds_read_b128 v[206:209], v0 offset:2048
	ds_read_b128 v[210:213], v0 offset:3072
	s_add_u32 s12, s48, 0x40000
	s_addc_u32 s13, s49, 0
	s_mov_b32 m0, s97
	v_lshl_add_u64 v[252:253], s[12:13], 0, v[146:147]
	ds_read_b128 v[214:217], v192 offset:32768
	ds_read_b128 v[218:221], v192 offset:33792
	ds_read_b128 v[222:225], v192 offset:34816
	ds_read_b128 v[226:229], v192 offset:35840
	ds_read_b128 v[230:233], v192 offset:36864
	ds_read_b128 v[234:237], v192 offset:37888
	ds_read_b128 v[238:241], v192 offset:38912
	ds_read_b128 v[242:245], v192 offset:39936
	global_load_lds_dwordx4 v[252:253], off
	v_lshl_add_u64 v[252:253], s[12:13], 0, v[150:151]
	s_mov_b32 m0, s76
	s_nop 0
	global_load_lds_dwordx4 v[252:253], off
	s_waitcnt vmcnt(8)
	s_waitcnt lgkmcnt(0)
	s_barrier
	s_setprio 1
	s_waitcnt lgkmcnt(0)
	v_mfma_f32_16x16x32_bf16 v[142:145], v[58:61], v[214:217], v[142:145]
	v_mfma_f32_16x16x32_bf16 v[138:141], v[66:69], v[214:217], v[138:141]
	v_mfma_f32_16x16x32_bf16 v[126:129], v[58:61], v[222:225], v[126:129]
	v_mfma_f32_16x16x32_bf16 v[122:125], v[66:69], v[222:225], v[122:125]
	v_mfma_f32_16x16x32_bf16 v[110:113], v[58:61], v[230:233], v[110:113]
	v_mfma_f32_16x16x32_bf16 v[106:109], v[66:69], v[230:233], v[106:109]
	v_mfma_f32_16x16x32_bf16 v[94:97], v[58:61], v[238:241], v[94:97]
	v_mfma_f32_16x16x32_bf16 v[90:93], v[66:69], v[238:241], v[90:93]
	v_mfma_f32_16x16x32_bf16 v[142:145], v[62:65], v[218:221], v[142:145]
	v_mfma_f32_16x16x32_bf16 v[138:141], v[70:73], v[218:221], v[138:141]
	v_mfma_f32_16x16x32_bf16 v[126:129], v[62:65], v[226:229], v[126:129]
	v_mfma_f32_16x16x32_bf16 v[122:125], v[70:73], v[226:229], v[122:125]
	v_mfma_f32_16x16x32_bf16 v[110:113], v[62:65], v[234:237], v[110:113]
	v_mfma_f32_16x16x32_bf16 v[106:109], v[70:73], v[234:237], v[106:109]
	v_mfma_f32_16x16x32_bf16 v[94:97], v[62:65], v[242:245], v[94:97]
	v_mfma_f32_16x16x32_bf16 v[90:93], v[70:73], v[242:245], v[90:93]
	v_mfma_f32_16x16x32_bf16 v[134:137], v[184:187], v[214:217], v[134:137]
	v_mfma_f32_16x16x32_bf16 v[130:133], v[206:209], v[214:217], v[130:133]
	v_mfma_f32_16x16x32_bf16 v[118:121], v[184:187], v[222:225], v[118:121]
	v_mfma_f32_16x16x32_bf16 v[114:117], v[206:209], v[222:225], v[114:117]
	v_mfma_f32_16x16x32_bf16 v[102:105], v[184:187], v[230:233], v[102:105]
	v_mfma_f32_16x16x32_bf16 v[98:101], v[206:209], v[230:233], v[98:101]
	v_mfma_f32_16x16x32_bf16 v[86:89], v[184:187], v[238:241], v[86:89]
	v_mfma_f32_16x16x32_bf16 v[82:85], v[206:209], v[238:241], v[82:85]
	v_mfma_f32_16x16x32_bf16 v[134:137], v[202:205], v[218:221], v[134:137]
	v_mfma_f32_16x16x32_bf16 v[130:133], v[210:213], v[218:221], v[130:133]
	v_mfma_f32_16x16x32_bf16 v[118:121], v[202:205], v[226:229], v[118:121]
	v_mfma_f32_16x16x32_bf16 v[114:117], v[210:213], v[226:229], v[114:117]
	v_mfma_f32_16x16x32_bf16 v[102:105], v[202:205], v[234:237], v[102:105]
	v_mfma_f32_16x16x32_bf16 v[98:101], v[210:213], v[234:237], v[98:101]
	v_mfma_f32_16x16x32_bf16 v[86:89], v[202:205], v[242:245], v[86:89]
	v_mfma_f32_16x16x32_bf16 v[82:85], v[210:213], v[242:245], v[82:85]
	s_setprio 0
	s_barrier
	s_add_i32 s12, s15, s81
	v_lshl_add_u64 v[200:201], v[200:201], 0, s[94:95]
	s_mov_b32 m0, s12
	ds_read_b128 v[214:217], v192 offset:49152
	ds_read_b128 v[218:221], v192 offset:50176
	ds_read_b128 v[222:225], v192 offset:51200
	ds_read_b128 v[226:229], v192 offset:52224
	ds_read_b128 v[230:233], v192 offset:53248
	ds_read_b128 v[234:237], v192 offset:54272
	ds_read_b128 v[238:241], v192 offset:55296
	ds_read_b128 v[242:245], v192 offset:56320
	global_load_lds_dwordx4 v[200:201], off
	s_add_i32 m0, s12, 0x2000
	s_add_u32 s12, s46, 0x40080
	v_lshl_add_u64 v[200:201], v[246:247], 0, s[94:95]
	s_addc_u32 s13, s47, 0
	s_add_i32 s15, s50, s81
	global_load_lds_dwordx4 v[200:201], off
	v_lshl_add_u64 v[200:201], s[12:13], 0, v[148:149]
	s_mov_b32 m0, s15
	s_nop 0
	global_load_lds_dwordx4 v[200:201], off
	v_lshl_add_u64 v[200:201], s[12:13], 0, v[152:153]
	s_add_i32 m0, s15, 0x2000
	s_nop 0
	global_load_lds_dwordx4 v[200:201], off
	v_lshl_add_u64 v[200:201], v[248:249], 0, s[94:95]
	s_mov_b32 m0, s33
	s_nop 0
	global_load_lds_dwordx4 v[200:201], off
	v_lshl_add_u64 v[200:201], v[250:251], 0, s[94:95]
	s_mov_b32 m0, s89
	s_nop 0
	global_load_lds_dwordx4 v[200:201], off
	s_waitcnt vmcnt(8)
	s_waitcnt lgkmcnt(0)
	s_barrier
	s_setprio 1
	s_waitcnt lgkmcnt(0)
	v_mfma_f32_16x16x32_bf16 v[78:81], v[58:61], v[214:217], v[78:81]
	v_mfma_f32_16x16x32_bf16 v[74:77], v[66:69], v[214:217], v[74:77]
	v_mfma_f32_16x16x32_bf16 v[50:53], v[58:61], v[222:225], v[50:53]
	v_mfma_f32_16x16x32_bf16 v[46:49], v[66:69], v[222:225], v[46:49]
	v_mfma_f32_16x16x32_bf16 v[30:33], v[58:61], v[230:233], v[30:33]
	v_mfma_f32_16x16x32_bf16 v[26:29], v[66:69], v[230:233], v[26:29]
	v_mfma_f32_16x16x32_bf16 v[14:17], v[58:61], v[238:241], v[14:17]
	v_mfma_f32_16x16x32_bf16 v[10:13], v[66:69], v[238:241], v[10:13]
	v_mfma_f32_16x16x32_bf16 v[78:81], v[62:65], v[218:221], v[78:81]
	v_mfma_f32_16x16x32_bf16 v[74:77], v[70:73], v[218:221], v[74:77]
	v_mfma_f32_16x16x32_bf16 v[50:53], v[62:65], v[226:229], v[50:53]
	v_mfma_f32_16x16x32_bf16 v[46:49], v[70:73], v[226:229], v[46:49]
	v_mfma_f32_16x16x32_bf16 v[30:33], v[62:65], v[234:237], v[30:33]
	v_mfma_f32_16x16x32_bf16 v[26:29], v[70:73], v[234:237], v[26:29]
	v_mfma_f32_16x16x32_bf16 v[14:17], v[62:65], v[242:245], v[14:17]
	v_mfma_f32_16x16x32_bf16 v[10:13], v[70:73], v[242:245], v[10:13]
	v_mfma_f32_16x16x32_bf16 v[42:45], v[184:187], v[214:217], v[42:45]
	v_mfma_f32_16x16x32_bf16 v[66:69], v[202:205], v[218:221], v[42:45]
	v_mfma_f32_16x16x32_bf16 v[42:45], v[206:209], v[214:217], v[54:57]
	v_mfma_f32_16x16x32_bf16 v[38:41], v[184:187], v[222:225], v[38:41]
	v_mfma_f32_16x16x32_bf16 v[34:37], v[206:209], v[222:225], v[34:37]
	v_mfma_f32_16x16x32_bf16 v[22:25], v[184:187], v[230:233], v[22:25]
	v_mfma_f32_16x16x32_bf16 v[18:21], v[206:209], v[230:233], v[18:21]
	v_mfma_f32_16x16x32_bf16 v[6:9], v[184:187], v[238:241], v[6:9]
	v_mfma_f32_16x16x32_bf16 v[2:5], v[206:209], v[238:241], v[2:5]
	v_mfma_f32_16x16x32_bf16 v[62:65], v[210:213], v[218:221], v[42:45]
	v_mfma_f32_16x16x32_bf16 v[38:41], v[202:205], v[226:229], v[38:41]
	v_mfma_f32_16x16x32_bf16 v[34:37], v[210:213], v[226:229], v[34:37]
	v_mfma_f32_16x16x32_bf16 v[22:25], v[202:205], v[234:237], v[22:25]
	v_mfma_f32_16x16x32_bf16 v[18:21], v[210:213], v[234:237], v[18:21]
	v_mfma_f32_16x16x32_bf16 v[6:9], v[202:205], v[242:245], v[6:9]
	v_mfma_f32_16x16x32_bf16 v[2:5], v[210:213], v[242:245], v[2:5]
	s_setprio 0
	s_barrier
	s_add_i32 vcc_lo, vcc_lo, 2
	s_add_u32 s85, s85, 0x100
	s_addc_u32 s90, s90, 0
	s_add_u32 s42, s42, 0x100
	s_addc_u32 s43, s43, 0
	s_cmp_gt_u32 vcc_lo, 13
	s_cbranch_scc0 .LBB0_183
	s_and_b64 vcc, exec, s[20:21]
	s_cbranch_vccz .LBB0_186
	s_barrier

.LBB0_382:
	s_add_u32 s12, s30, 0xfffc0080
	s_addc_u32 s13, s31, -1
	s_add_i32 s15, 0, 0x10000
	s_cmp_eq_u32 s76, 12
	s_cselect_b32 s43, s9, s13
	s_cselect_b32 s42, s11, s12
	v_add_u32_e32 v0, s15, v156
	s_cselect_b32 s35, s14, s33
	s_cselect_b32 s34, s23, s25
	s_add_i32 s50, 0, 0x14000
	ds_read_b128 v[148:151], v0
	ds_read_b128 v[152:155], v0 offset:1024
	ds_read_b128 v[182:185], v0 offset:2048
	ds_read_b128 v[186:189], v0 offset:3072
	v_add_u32_e32 v0, s50, v156
	ds_read_b128 v[190:193], v0
	ds_read_b128 v[202:205], v0 offset:1024
	ds_read_b128 v[206:209], v0 offset:2048
	ds_read_b128 v[210:213], v0 offset:3072
	v_lshl_add_u64 v[200:201], s[30:31], 0, v[146:147]
	s_add_i32 m0, s48, 0xc000
	ds_read_b128 v[214:217], v157
	ds_read_b128 v[218:221], v157 offset:1024
	ds_read_b128 v[222:225], v157 offset:2048
	ds_read_b128 v[226:229], v157 offset:3072
	ds_read_b128 v[230:233], v157 offset:4096
	ds_read_b128 v[234:237], v157 offset:5120
	ds_read_b128 v[238:241], v157 offset:6144
	ds_read_b128 v[242:245], v157 offset:7168
	global_load_lds_dwordx4 v[200:201], off
	v_lshl_add_u64 v[200:201], s[30:31], 0, v[144:145]
	s_add_i32 m0, s48, 0xe000
	s_nop 0
	global_load_lds_dwordx4 v[200:201], off
	s_waitcnt vmcnt(8)
	s_waitcnt lgkmcnt(0)
	s_barrier
	s_setprio 1
	s_waitcnt lgkmcnt(0)
	v_mfma_f32_16x16x32_bf16 v[126:129], v[148:151], v[214:217], v[126:129]
	v_mfma_f32_16x16x32_bf16 v[122:125], v[182:185], v[214:217], v[122:125]
	v_mfma_f32_16x16x32_bf16 v[110:113], v[148:151], v[222:225], v[110:113]
	v_mfma_f32_16x16x32_bf16 v[106:109], v[182:185], v[222:225], v[106:109]
	v_mfma_f32_16x16x32_bf16 v[94:97], v[148:151], v[230:233], v[94:97]
	v_mfma_f32_16x16x32_bf16 v[90:93], v[182:185], v[230:233], v[90:93]
	v_mfma_f32_16x16x32_bf16 v[78:81], v[148:151], v[238:241], v[78:81]
	v_mfma_f32_16x16x32_bf16 v[74:77], v[182:185], v[238:241], v[74:77]
	v_mfma_f32_16x16x32_bf16 v[126:129], v[152:155], v[218:221], v[126:129]
	v_mfma_f32_16x16x32_bf16 v[122:125], v[186:189], v[218:221], v[122:125]
	v_mfma_f32_16x16x32_bf16 v[110:113], v[152:155], v[226:229], v[110:113]
	v_mfma_f32_16x16x32_bf16 v[106:109], v[186:189], v[226:229], v[106:109]
	v_mfma_f32_16x16x32_bf16 v[94:97], v[152:155], v[234:237], v[94:97]
	v_mfma_f32_16x16x32_bf16 v[90:93], v[186:189], v[234:237], v[90:93]
	v_mfma_f32_16x16x32_bf16 v[78:81], v[152:155], v[242:245], v[78:81]
	v_mfma_f32_16x16x32_bf16 v[74:77], v[186:189], v[242:245], v[74:77]
	v_mfma_f32_16x16x32_bf16 v[118:121], v[190:193], v[214:217], v[118:121]
	v_mfma_f32_16x16x32_bf16 v[114:117], v[206:209], v[214:217], v[114:117]
	v_mfma_f32_16x16x32_bf16 v[102:105], v[190:193], v[222:225], v[102:105]
	v_mfma_f32_16x16x32_bf16 v[98:101], v[206:209], v[222:225], v[98:101]
	v_mfma_f32_16x16x32_bf16 v[86:89], v[190:193], v[230:233], v[86:89]
	v_mfma_f32_16x16x32_bf16 v[82:85], v[206:209], v[230:233], v[82:85]
	v_mfma_f32_16x16x32_bf16 v[70:73], v[190:193], v[238:241], v[70:73]
	v_mfma_f32_16x16x32_bf16 v[66:69], v[206:209], v[238:241], v[66:69]
	v_mfma_f32_16x16x32_bf16 v[118:121], v[202:205], v[218:221], v[118:121]
	v_mfma_f32_16x16x32_bf16 v[114:117], v[210:213], v[218:221], v[114:117]
	v_mfma_f32_16x16x32_bf16 v[102:105], v[202:205], v[226:229], v[102:105]
	v_mfma_f32_16x16x32_bf16 v[98:101], v[210:213], v[226:229], v[98:101]
	v_mfma_f32_16x16x32_bf16 v[86:89], v[202:205], v[234:237], v[86:89]
	v_mfma_f32_16x16x32_bf16 v[82:85], v[210:213], v[234:237], v[82:85]
	v_mfma_f32_16x16x32_bf16 v[70:73], v[202:205], v[242:245], v[70:73]
	v_mfma_f32_16x16x32_bf16 v[66:69], v[210:213], v[242:245], v[66:69]
	s_setprio 0
	s_barrier
	s_add_i32 s12, s15, s47
	v_lshl_add_u64 v[200:201], s[34:35], 0, v[132:133]
	s_mov_b32 m0, s12
	ds_read_b128 v[214:217], v157 offset:16384
	ds_read_b128 v[218:221], v157 offset:17408
	ds_read_b128 v[222:225], v157 offset:18432
	ds_read_b128 v[226:229], v157 offset:19456
	ds_read_b128 v[230:233], v157 offset:20480
	ds_read_b128 v[234:237], v157 offset:21504
	ds_read_b128 v[238:241], v157 offset:22528
	ds_read_b128 v[242:245], v157 offset:23552
	global_load_lds_dwordx4 v[200:201], off
	s_add_i32 m0, s12, 0x2000
	s_add_u32 s12, s34, 0x40000
	v_lshl_add_u64 v[246:247], s[34:35], 0, v[136:137]
	s_addc_u32 s13, s35, 0
	s_add_i32 s15, s50, s47
	global_load_lds_dwordx4 v[246:247], off
	v_lshl_add_u64 v[248:249], s[12:13], 0, v[132:133]
	s_mov_b32 m0, s15
	v_lshl_add_u64 v[250:251], s[42:43], 0, v[134:135]
	global_load_lds_dwordx4 v[248:249], off
	v_lshl_add_u64 v[248:249], s[12:13], 0, v[136:137]
	s_add_i32 m0, s15, 0x2000
	s_nop 0
	global_load_lds_dwordx4 v[248:249], off
	v_lshl_add_u64 v[248:249], s[42:43], 0, v[130:131]
	s_mov_b32 m0, s48
	s_nop 0
	global_load_lds_dwordx4 v[248:249], off
	s_mov_b32 m0, s49
	s_nop 0
	global_load_lds_dwordx4 v[250:251], off
	s_waitcnt vmcnt(8)
	s_waitcnt lgkmcnt(0)
	s_barrier
	s_setprio 1
	s_waitcnt lgkmcnt(0)
	v_mfma_f32_16x16x32_bf16 v[62:65], v[148:151], v[214:217], v[62:65]
	v_mfma_f32_16x16x32_bf16 v[58:61], v[182:185], v[214:217], v[58:61]
	v_mfma_f32_16x16x32_bf16 v[46:49], v[148:151], v[222:225], v[46:49]
	v_mfma_f32_16x16x32_bf16 v[42:45], v[182:185], v[222:225], v[42:45]
	v_mfma_f32_16x16x32_bf16 v[30:33], v[148:151], v[230:233], v[30:33]
	v_mfma_f32_16x16x32_bf16 v[26:29], v[182:185], v[230:233], v[26:29]
	v_mfma_f32_16x16x32_bf16 v[14:17], v[148:151], v[238:241], v[14:17]
	v_mfma_f32_16x16x32_bf16 v[10:13], v[182:185], v[238:241], v[10:13]
	v_mfma_f32_16x16x32_bf16 v[62:65], v[152:155], v[218:221], v[62:65]
	v_mfma_f32_16x16x32_bf16 v[58:61], v[186:189], v[218:221], v[58:61]
	v_mfma_f32_16x16x32_bf16 v[46:49], v[152:155], v[226:229], v[46:49]
	v_mfma_f32_16x16x32_bf16 v[42:45], v[186:189], v[226:229], v[42:45]
	v_mfma_f32_16x16x32_bf16 v[30:33], v[152:155], v[234:237], v[30:33]
	v_mfma_f32_16x16x32_bf16 v[26:29], v[186:189], v[234:237], v[26:29]
	v_mfma_f32_16x16x32_bf16 v[14:17], v[152:155], v[242:245], v[14:17]
	v_mfma_f32_16x16x32_bf16 v[10:13], v[186:189], v[242:245], v[10:13]
	v_mfma_f32_16x16x32_bf16 v[54:57], v[190:193], v[214:217], v[54:57]
	v_mfma_f32_16x16x32_bf16 v[50:53], v[206:209], v[214:217], v[50:53]
	v_mfma_f32_16x16x32_bf16 v[38:41], v[190:193], v[222:225], v[38:41]
	v_mfma_f32_16x16x32_bf16 v[34:37], v[206:209], v[222:225], v[34:37]
	v_mfma_f32_16x16x32_bf16 v[22:25], v[190:193], v[230:233], v[22:25]
	v_mfma_f32_16x16x32_bf16 v[18:21], v[206:209], v[230:233], v[18:21]
	v_mfma_f32_16x16x32_bf16 v[6:9], v[190:193], v[238:241], v[6:9]
	v_mfma_f32_16x16x32_bf16 v[2:5], v[206:209], v[238:241], v[2:5]
	v_mfma_f32_16x16x32_bf16 v[54:57], v[202:205], v[218:221], v[54:57]
	v_mfma_f32_16x16x32_bf16 v[50:53], v[210:213], v[218:221], v[50:53]
	v_mfma_f32_16x16x32_bf16 v[38:41], v[202:205], v[226:229], v[38:41]
	v_mfma_f32_16x16x32_bf16 v[34:37], v[210:213], v[226:229], v[34:37]
	v_mfma_f32_16x16x32_bf16 v[22:25], v[202:205], v[234:237], v[22:25]
	v_mfma_f32_16x16x32_bf16 v[18:21], v[210:213], v[234:237], v[18:21]
	v_mfma_f32_16x16x32_bf16 v[6:9], v[202:205], v[242:245], v[6:9]
	v_mfma_f32_16x16x32_bf16 v[2:5], v[210:213], v[242:245], v[2:5]
	s_setprio 0
	s_barrier
	s_add_i32 s15, 0, 0x18000
	v_add_u32_e32 v0, s15, v156
	s_add_i32 s50, 0, 0x1c000
	ds_read_b128 v[148:151], v0
	ds_read_b128 v[152:155], v0 offset:1024
	ds_read_b128 v[182:185], v0 offset:2048
	ds_read_b128 v[186:189], v0 offset:3072
	v_add_u32_e32 v0, s50, v156
	ds_read_b128 v[190:193], v0
	ds_read_b128 v[202:205], v0 offset:1024
	ds_read_b128 v[206:209], v0 offset:2048
	ds_read_b128 v[210:213], v0 offset:3072
	s_add_u32 s12, s42, 0x40000
	s_addc_u32 s13, s43, 0
	s_mov_b32 m0, s90
	v_lshl_add_u64 v[252:253], s[12:13], 0, v[130:131]
	ds_read_b128 v[214:217], v157 offset:32768
	ds_read_b128 v[218:221], v157 offset:33792
	ds_read_b128 v[222:225], v157 offset:34816
	ds_read_b128 v[226:229], v157 offset:35840
	ds_read_b128 v[230:233], v157 offset:36864
	ds_read_b128 v[234:237], v157 offset:37888
	ds_read_b128 v[238:241], v157 offset:38912
	ds_read_b128 v[242:245], v157 offset:39936
	global_load_lds_dwordx4 v[252:253], off
	v_lshl_add_u64 v[252:253], s[12:13], 0, v[134:135]
	s_mov_b32 m0, s96
	s_nop 0
	global_load_lds_dwordx4 v[252:253], off
	s_waitcnt vmcnt(8)
	s_waitcnt lgkmcnt(0)
	s_barrier
	s_setprio 1
	s_waitcnt lgkmcnt(0)
	v_mfma_f32_16x16x32_bf16 v[126:129], v[148:151], v[214:217], v[126:129]
	v_mfma_f32_16x16x32_bf16 v[122:125], v[182:185], v[214:217], v[122:125]
	v_mfma_f32_16x16x32_bf16 v[110:113], v[148:151], v[222:225], v[110:113]
	v_mfma_f32_16x16x32_bf16 v[106:109], v[182:185], v[222:225], v[106:109]
	v_mfma_f32_16x16x32_bf16 v[94:97], v[148:151], v[230:233], v[94:97]
	v_mfma_f32_16x16x32_bf16 v[90:93], v[182:185], v[230:233], v[90:93]
	v_mfma_f32_16x16x32_bf16 v[78:81], v[148:151], v[238:241], v[78:81]
	v_mfma_f32_16x16x32_bf16 v[74:77], v[182:185], v[238:241], v[74:77]
	v_mfma_f32_16x16x32_bf16 v[126:129], v[152:155], v[218:221], v[126:129]
	v_mfma_f32_16x16x32_bf16 v[122:125], v[186:189], v[218:221], v[122:125]
	v_mfma_f32_16x16x32_bf16 v[110:113], v[152:155], v[226:229], v[110:113]
	v_mfma_f32_16x16x32_bf16 v[106:109], v[186:189], v[226:229], v[106:109]
	v_mfma_f32_16x16x32_bf16 v[94:97], v[152:155], v[234:237], v[94:97]
	v_mfma_f32_16x16x32_bf16 v[90:93], v[186:189], v[234:237], v[90:93]
	v_mfma_f32_16x16x32_bf16 v[78:81], v[152:155], v[242:245], v[78:81]
	v_mfma_f32_16x16x32_bf16 v[74:77], v[186:189], v[242:245], v[74:77]
	v_mfma_f32_16x16x32_bf16 v[118:121], v[190:193], v[214:217], v[118:121]
	v_mfma_f32_16x16x32_bf16 v[114:117], v[206:209], v[214:217], v[114:117]
	v_mfma_f32_16x16x32_bf16 v[102:105], v[190:193], v[222:225], v[102:105]
	v_mfma_f32_16x16x32_bf16 v[98:101], v[206:209], v[222:225], v[98:101]
	v_mfma_f32_16x16x32_bf16 v[86:89], v[190:193], v[230:233], v[86:89]
	v_mfma_f32_16x16x32_bf16 v[82:85], v[206:209], v[230:233], v[82:85]
	v_mfma_f32_16x16x32_bf16 v[70:73], v[190:193], v[238:241], v[70:73]
	v_mfma_f32_16x16x32_bf16 v[66:69], v[206:209], v[238:241], v[66:69]
	v_mfma_f32_16x16x32_bf16 v[118:121], v[202:205], v[218:221], v[118:121]
	v_mfma_f32_16x16x32_bf16 v[114:117], v[210:213], v[218:221], v[114:117]
	v_mfma_f32_16x16x32_bf16 v[102:105], v[202:205], v[226:229], v[102:105]
	v_mfma_f32_16x16x32_bf16 v[98:101], v[210:213], v[226:229], v[98:101]
	v_mfma_f32_16x16x32_bf16 v[86:89], v[202:205], v[234:237], v[86:89]
	v_mfma_f32_16x16x32_bf16 v[82:85], v[210:213], v[234:237], v[82:85]
	v_mfma_f32_16x16x32_bf16 v[70:73], v[202:205], v[242:245], v[70:73]
	v_mfma_f32_16x16x32_bf16 v[66:69], v[210:213], v[242:245], v[66:69]
	s_setprio 0
	s_barrier
	s_add_i32 s12, s15, s47
	v_lshl_add_u64 v[200:201], v[200:201], 0, s[94:95]
	s_mov_b32 m0, s12
	ds_read_b128 v[214:217], v157 offset:49152
	ds_read_b128 v[218:221], v157 offset:50176
	ds_read_b128 v[222:225], v157 offset:51200
	ds_read_b128 v[226:229], v157 offset:52224
	ds_read_b128 v[230:233], v157 offset:53248
	ds_read_b128 v[234:237], v157 offset:54272
	ds_read_b128 v[238:241], v157 offset:55296
	ds_read_b128 v[242:245], v157 offset:56320
	global_load_lds_dwordx4 v[200:201], off
	s_add_i32 m0, s12, 0x2000
	s_add_u32 s12, s34, 0x40080
	v_lshl_add_u64 v[200:201], v[246:247], 0, s[94:95]
	s_addc_u32 s13, s35, 0
	s_add_i32 s15, s50, s47
	global_load_lds_dwordx4 v[200:201], off
	v_lshl_add_u64 v[200:201], s[12:13], 0, v[132:133]
	s_mov_b32 m0, s15
	s_nop 0
	global_load_lds_dwordx4 v[200:201], off
	v_lshl_add_u64 v[200:201], s[12:13], 0, v[136:137]
	s_add_i32 m0, s15, 0x2000
	s_nop 0
	global_load_lds_dwordx4 v[200:201], off
	v_lshl_add_u64 v[200:201], v[248:249], 0, s[94:95]
	s_mov_b32 m0, s80
	s_nop 0
	global_load_lds_dwordx4 v[200:201], off
	v_lshl_add_u64 v[200:201], v[250:251], 0, s[94:95]
	s_mov_b32 m0, s81
	s_nop 0
	global_load_lds_dwordx4 v[200:201], off
	s_waitcnt vmcnt(8)
	s_waitcnt lgkmcnt(0)
	s_barrier
	s_setprio 1
	s_waitcnt lgkmcnt(0)
	v_mfma_f32_16x16x32_bf16 v[62:65], v[148:151], v[214:217], v[62:65]
	v_mfma_f32_16x16x32_bf16 v[58:61], v[182:185], v[214:217], v[58:61]
	v_mfma_f32_16x16x32_bf16 v[46:49], v[148:151], v[222:225], v[46:49]
	v_mfma_f32_16x16x32_bf16 v[42:45], v[182:185], v[222:225], v[42:45]
	v_mfma_f32_16x16x32_bf16 v[30:33], v[148:151], v[230:233], v[30:33]
	v_mfma_f32_16x16x32_bf16 v[26:29], v[182:185], v[230:233], v[26:29]
	v_mfma_f32_16x16x32_bf16 v[14:17], v[148:151], v[238:241], v[14:17]
	v_mfma_f32_16x16x32_bf16 v[10:13], v[182:185], v[238:241], v[10:13]
	v_mfma_f32_16x16x32_bf16 v[62:65], v[152:155], v[218:221], v[62:65]
	v_mfma_f32_16x16x32_bf16 v[58:61], v[186:189], v[218:221], v[58:61]
	v_mfma_f32_16x16x32_bf16 v[46:49], v[152:155], v[226:229], v[46:49]
	v_mfma_f32_16x16x32_bf16 v[42:45], v[186:189], v[226:229], v[42:45]
	v_mfma_f32_16x16x32_bf16 v[30:33], v[152:155], v[234:237], v[30:33]
	v_mfma_f32_16x16x32_bf16 v[26:29], v[186:189], v[234:237], v[26:29]
	v_mfma_f32_16x16x32_bf16 v[14:17], v[152:155], v[242:245], v[14:17]
	v_mfma_f32_16x16x32_bf16 v[10:13], v[186:189], v[242:245], v[10:13]
	v_mfma_f32_16x16x32_bf16 v[54:57], v[190:193], v[214:217], v[54:57]
	v_mfma_f32_16x16x32_bf16 v[50:53], v[206:209], v[214:217], v[50:53]
	v_mfma_f32_16x16x32_bf16 v[38:41], v[190:193], v[222:225], v[38:41]
	v_mfma_f32_16x16x32_bf16 v[34:37], v[206:209], v[222:225], v[34:37]
	v_mfma_f32_16x16x32_bf16 v[22:25], v[190:193], v[230:233], v[22:25]
	v_mfma_f32_16x16x32_bf16 v[18:21], v[206:209], v[230:233], v[18:21]
	v_mfma_f32_16x16x32_bf16 v[6:9], v[190:193], v[238:241], v[6:9]
	v_mfma_f32_16x16x32_bf16 v[2:5], v[206:209], v[238:241], v[2:5]
	v_mfma_f32_16x16x32_bf16 v[54:57], v[202:205], v[218:221], v[54:57]
	v_mfma_f32_16x16x32_bf16 v[50:53], v[210:213], v[218:221], v[50:53]
	v_mfma_f32_16x16x32_bf16 v[38:41], v[202:205], v[226:229], v[38:41]
	v_mfma_f32_16x16x32_bf16 v[34:37], v[210:213], v[226:229], v[34:37]
	v_mfma_f32_16x16x32_bf16 v[22:25], v[202:205], v[234:237], v[22:25]
	v_mfma_f32_16x16x32_bf16 v[18:21], v[210:213], v[234:237], v[18:21]
	v_mfma_f32_16x16x32_bf16 v[6:9], v[202:205], v[242:245], v[6:9]
	v_mfma_f32_16x16x32_bf16 v[2:5], v[210:213], v[242:245], v[2:5]
	s_setprio 0
	s_barrier
	s_add_i32 s76, s76, 2
	s_add_u32 s25, s25, 0x100
	s_addc_u32 s33, s33, 0
	s_add_u32 s30, s30, 0x100
	s_addc_u32 s31, s31, 0
	s_cmp_gt_u32 s76, 13
	s_cbranch_scc0 .LBB0_382
	s_and_b64 vcc, exec, s[20:21]
	s_cbranch_vccz .LBB0_385
	s_barrier

.LBB0_544:
	s_add_u32 s8, s6, 0x100
	s_addc_u32 s9, s7, 0
	s_add_i32 s12, 0, 0x10000
	s_cmp_eq_u32 s85, 2
	s_cselect_b32 s27, s1, s9
	s_cselect_b32 s26, s0, s8
	v_add_u32_e32 v0, s12, v152
	s_cselect_b32 s25, s23, s84
	s_cselect_b32 s24, s22, s76
	s_add_i32 s13, 0, 0x14000
	ds_read_b128 v[146:149], v0
	ds_read_b128 v[154:157], v0 offset:1024
	ds_read_b128 v[182:185], v0 offset:2048
	ds_read_b128 v[186:189], v0 offset:3072
	v_add_u32_e32 v0, s13, v152
	ds_read_b128 v[190:193], v0
	ds_read_b128 v[202:205], v0 offset:1024
	ds_read_b128 v[206:209], v0 offset:2048
	ds_read_b128 v[210:213], v0 offset:3072
	v_lshl_add_u64 v[150:151], s[6:7], 0, v[144:145]
	s_add_i32 m0, s30, 0xc000
	ds_read_b128 v[214:217], v153
	ds_read_b128 v[218:221], v153 offset:1024
	ds_read_b128 v[222:225], v153 offset:2048
	ds_read_b128 v[226:229], v153 offset:3072
	ds_read_b128 v[230:233], v153 offset:4096
	ds_read_b128 v[234:237], v153 offset:5120
	ds_read_b128 v[238:241], v153 offset:6144
	ds_read_b128 v[242:245], v153 offset:7168
	global_load_lds_dwordx4 v[150:151], off
	v_lshl_add_u64 v[150:151], s[6:7], 0, v[142:143]
	s_add_i32 m0, s30, 0xe000
	s_nop 0
	global_load_lds_dwordx4 v[150:151], off
	s_waitcnt vmcnt(8)
	s_waitcnt lgkmcnt(0)
	s_barrier
	s_setprio 1
	s_waitcnt lgkmcnt(0)
	v_mfma_f32_16x16x32_bf16 v[126:129], v[146:149], v[214:217], v[126:129]
	v_mfma_f32_16x16x32_bf16 v[122:125], v[182:185], v[214:217], v[122:125]
	v_mfma_f32_16x16x32_bf16 v[110:113], v[146:149], v[222:225], v[110:113]
	v_mfma_f32_16x16x32_bf16 v[106:109], v[182:185], v[222:225], v[106:109]
	v_mfma_f32_16x16x32_bf16 v[94:97], v[146:149], v[230:233], v[94:97]
	v_mfma_f32_16x16x32_bf16 v[90:93], v[182:185], v[230:233], v[90:93]
	v_mfma_f32_16x16x32_bf16 v[78:81], v[146:149], v[238:241], v[78:81]
	v_mfma_f32_16x16x32_bf16 v[74:77], v[182:185], v[238:241], v[74:77]
	v_mfma_f32_16x16x32_bf16 v[126:129], v[154:157], v[218:221], v[126:129]
	v_mfma_f32_16x16x32_bf16 v[122:125], v[186:189], v[218:221], v[122:125]
	v_mfma_f32_16x16x32_bf16 v[110:113], v[154:157], v[226:229], v[110:113]
	v_mfma_f32_16x16x32_bf16 v[106:109], v[186:189], v[226:229], v[106:109]
	v_mfma_f32_16x16x32_bf16 v[94:97], v[154:157], v[234:237], v[94:97]
	v_mfma_f32_16x16x32_bf16 v[90:93], v[186:189], v[234:237], v[90:93]
	v_mfma_f32_16x16x32_bf16 v[78:81], v[154:157], v[242:245], v[78:81]
	v_mfma_f32_16x16x32_bf16 v[74:77], v[186:189], v[242:245], v[74:77]
	v_mfma_f32_16x16x32_bf16 v[118:121], v[190:193], v[214:217], v[118:121]
	v_mfma_f32_16x16x32_bf16 v[114:117], v[206:209], v[214:217], v[114:117]
	v_mfma_f32_16x16x32_bf16 v[102:105], v[190:193], v[222:225], v[102:105]
	v_mfma_f32_16x16x32_bf16 v[98:101], v[206:209], v[222:225], v[98:101]
	v_mfma_f32_16x16x32_bf16 v[86:89], v[190:193], v[230:233], v[86:89]
	v_mfma_f32_16x16x32_bf16 v[82:85], v[206:209], v[230:233], v[82:85]
	v_mfma_f32_16x16x32_bf16 v[70:73], v[190:193], v[238:241], v[70:73]
	v_mfma_f32_16x16x32_bf16 v[66:69], v[206:209], v[238:241], v[66:69]
	v_mfma_f32_16x16x32_bf16 v[118:121], v[202:205], v[218:221], v[118:121]
	v_mfma_f32_16x16x32_bf16 v[114:117], v[210:213], v[218:221], v[114:117]
	v_mfma_f32_16x16x32_bf16 v[102:105], v[202:205], v[226:229], v[102:105]
	v_mfma_f32_16x16x32_bf16 v[98:101], v[210:213], v[226:229], v[98:101]
	v_mfma_f32_16x16x32_bf16 v[86:89], v[202:205], v[234:237], v[86:89]
	v_mfma_f32_16x16x32_bf16 v[82:85], v[210:213], v[234:237], v[82:85]
	v_mfma_f32_16x16x32_bf16 v[70:73], v[202:205], v[242:245], v[70:73]
	v_mfma_f32_16x16x32_bf16 v[66:69], v[210:213], v[242:245], v[66:69]
	s_setprio 0
	s_barrier
	s_add_i32 s6, s12, s29
	v_lshl_add_u64 v[150:151], s[24:25], 0, v[132:133]
	s_mov_b32 m0, s6
	ds_read_b128 v[214:217], v153 offset:16384
	ds_read_b128 v[218:221], v153 offset:17408
	ds_read_b128 v[222:225], v153 offset:18432
	ds_read_b128 v[226:229], v153 offset:19456
	ds_read_b128 v[230:233], v153 offset:20480
	ds_read_b128 v[234:237], v153 offset:21504
	ds_read_b128 v[238:241], v153 offset:22528
	ds_read_b128 v[242:245], v153 offset:23552
	global_load_lds_dwordx4 v[150:151], off
	s_add_i32 m0, s6, 0x2000
	s_add_u32 s6, s24, 0x18000
	v_lshl_add_u64 v[200:201], s[24:25], 0, v[136:137]
	s_addc_u32 s7, s25, 0
	s_add_i32 s12, s13, s29
	global_load_lds_dwordx4 v[200:201], off
	v_lshl_add_u64 v[246:247], s[6:7], 0, v[132:133]
	s_mov_b32 m0, s12
	v_lshl_add_u64 v[248:249], s[26:27], 0, v[134:135]
	global_load_lds_dwordx4 v[246:247], off
	v_lshl_add_u64 v[246:247], s[6:7], 0, v[136:137]
	s_add_i32 m0, s12, 0x2000
	s_nop 0
	global_load_lds_dwordx4 v[246:247], off
	v_lshl_add_u64 v[246:247], s[26:27], 0, v[130:131]
	s_mov_b32 m0, s30
	s_nop 0
	global_load_lds_dwordx4 v[246:247], off
	s_mov_b32 m0, s31
	s_nop 0
	global_load_lds_dwordx4 v[248:249], off
	s_waitcnt vmcnt(8)
	s_waitcnt lgkmcnt(0)
	s_barrier
	s_setprio 1
	s_waitcnt lgkmcnt(0)
	v_mfma_f32_16x16x32_bf16 v[62:65], v[146:149], v[214:217], v[62:65]
	v_mfma_f32_16x16x32_bf16 v[58:61], v[182:185], v[214:217], v[58:61]
	v_mfma_f32_16x16x32_bf16 v[46:49], v[146:149], v[222:225], v[46:49]
	v_mfma_f32_16x16x32_bf16 v[42:45], v[182:185], v[222:225], v[42:45]
	v_mfma_f32_16x16x32_bf16 v[30:33], v[146:149], v[230:233], v[30:33]
	v_mfma_f32_16x16x32_bf16 v[26:29], v[182:185], v[230:233], v[26:29]
	v_mfma_f32_16x16x32_bf16 v[14:17], v[146:149], v[238:241], v[14:17]
	v_mfma_f32_16x16x32_bf16 v[10:13], v[182:185], v[238:241], v[10:13]
	v_mfma_f32_16x16x32_bf16 v[62:65], v[154:157], v[218:221], v[62:65]
	v_mfma_f32_16x16x32_bf16 v[58:61], v[186:189], v[218:221], v[58:61]
	v_mfma_f32_16x16x32_bf16 v[46:49], v[154:157], v[226:229], v[46:49]
	v_mfma_f32_16x16x32_bf16 v[42:45], v[186:189], v[226:229], v[42:45]
	v_mfma_f32_16x16x32_bf16 v[30:33], v[154:157], v[234:237], v[30:33]
	v_mfma_f32_16x16x32_bf16 v[26:29], v[186:189], v[234:237], v[26:29]
	v_mfma_f32_16x16x32_bf16 v[14:17], v[154:157], v[242:245], v[14:17]
	v_mfma_f32_16x16x32_bf16 v[10:13], v[186:189], v[242:245], v[10:13]
	v_mfma_f32_16x16x32_bf16 v[54:57], v[190:193], v[214:217], v[54:57]
	v_mfma_f32_16x16x32_bf16 v[50:53], v[206:209], v[214:217], v[50:53]
	v_mfma_f32_16x16x32_bf16 v[38:41], v[190:193], v[222:225], v[38:41]
	v_mfma_f32_16x16x32_bf16 v[34:37], v[206:209], v[222:225], v[34:37]
	v_mfma_f32_16x16x32_bf16 v[22:25], v[190:193], v[230:233], v[22:25]
	v_mfma_f32_16x16x32_bf16 v[18:21], v[206:209], v[230:233], v[18:21]
	v_mfma_f32_16x16x32_bf16 v[6:9], v[190:193], v[238:241], v[6:9]
	v_mfma_f32_16x16x32_bf16 v[2:5], v[206:209], v[238:241], v[2:5]
	v_mfma_f32_16x16x32_bf16 v[54:57], v[202:205], v[218:221], v[54:57]
	v_mfma_f32_16x16x32_bf16 v[50:53], v[210:213], v[218:221], v[50:53]
	v_mfma_f32_16x16x32_bf16 v[38:41], v[202:205], v[226:229], v[38:41]
	v_mfma_f32_16x16x32_bf16 v[34:37], v[210:213], v[226:229], v[34:37]
	v_mfma_f32_16x16x32_bf16 v[22:25], v[202:205], v[234:237], v[22:25]
	v_mfma_f32_16x16x32_bf16 v[18:21], v[210:213], v[234:237], v[18:21]
	v_mfma_f32_16x16x32_bf16 v[6:9], v[202:205], v[242:245], v[6:9]
	v_mfma_f32_16x16x32_bf16 v[2:5], v[210:213], v[242:245], v[2:5]
	s_setprio 0
	s_barrier
	s_add_i32 s12, 0, 0x18000
	v_add_u32_e32 v0, s12, v152
	s_add_i32 s13, 0, 0x1c000
	ds_read_b128 v[146:149], v0
	ds_read_b128 v[154:157], v0 offset:1024
	ds_read_b128 v[182:185], v0 offset:2048
	ds_read_b128 v[186:189], v0 offset:3072
	v_add_u32_e32 v0, s13, v152
	ds_read_b128 v[190:193], v0
	ds_read_b128 v[202:205], v0 offset:1024
	ds_read_b128 v[206:209], v0 offset:2048
	ds_read_b128 v[210:213], v0 offset:3072
	s_add_u32 s6, s26, 0x30000
	s_addc_u32 s7, s27, 0
	s_mov_b32 m0, s34
	v_lshl_add_u64 v[250:251], s[6:7], 0, v[130:131]
	ds_read_b128 v[214:217], v153 offset:32768
	ds_read_b128 v[218:221], v153 offset:33792
	ds_read_b128 v[222:225], v153 offset:34816
	ds_read_b128 v[226:229], v153 offset:35840
	ds_read_b128 v[230:233], v153 offset:36864
	ds_read_b128 v[234:237], v153 offset:37888
	ds_read_b128 v[238:241], v153 offset:38912
	ds_read_b128 v[242:245], v153 offset:39936
	global_load_lds_dwordx4 v[250:251], off
	v_lshl_add_u64 v[250:251], s[6:7], 0, v[134:135]
	s_mov_b32 m0, s35
	s_nop 0
	global_load_lds_dwordx4 v[250:251], off
	s_waitcnt vmcnt(8)
	s_waitcnt lgkmcnt(0)
	s_barrier
	s_setprio 1
	s_waitcnt lgkmcnt(0)
	v_mfma_f32_16x16x32_bf16 v[126:129], v[146:149], v[214:217], v[126:129]
	v_mfma_f32_16x16x32_bf16 v[122:125], v[182:185], v[214:217], v[122:125]
	v_mfma_f32_16x16x32_bf16 v[110:113], v[146:149], v[222:225], v[110:113]
	v_mfma_f32_16x16x32_bf16 v[106:109], v[182:185], v[222:225], v[106:109]
	v_mfma_f32_16x16x32_bf16 v[94:97], v[146:149], v[230:233], v[94:97]
	v_mfma_f32_16x16x32_bf16 v[90:93], v[182:185], v[230:233], v[90:93]
	v_mfma_f32_16x16x32_bf16 v[78:81], v[146:149], v[238:241], v[78:81]
	v_mfma_f32_16x16x32_bf16 v[74:77], v[182:185], v[238:241], v[74:77]
	v_mfma_f32_16x16x32_bf16 v[126:129], v[154:157], v[218:221], v[126:129]
	v_mfma_f32_16x16x32_bf16 v[122:125], v[186:189], v[218:221], v[122:125]
	v_mfma_f32_16x16x32_bf16 v[110:113], v[154:157], v[226:229], v[110:113]
	v_mfma_f32_16x16x32_bf16 v[106:109], v[186:189], v[226:229], v[106:109]
	v_mfma_f32_16x16x32_bf16 v[94:97], v[154:157], v[234:237], v[94:97]
	v_mfma_f32_16x16x32_bf16 v[90:93], v[186:189], v[234:237], v[90:93]
	v_mfma_f32_16x16x32_bf16 v[78:81], v[154:157], v[242:245], v[78:81]
	v_mfma_f32_16x16x32_bf16 v[74:77], v[186:189], v[242:245], v[74:77]
	v_mfma_f32_16x16x32_bf16 v[118:121], v[190:193], v[214:217], v[118:121]
	v_mfma_f32_16x16x32_bf16 v[114:117], v[206:209], v[214:217], v[114:117]
	v_mfma_f32_16x16x32_bf16 v[102:105], v[190:193], v[222:225], v[102:105]
	v_mfma_f32_16x16x32_bf16 v[98:101], v[206:209], v[222:225], v[98:101]
	v_mfma_f32_16x16x32_bf16 v[86:89], v[190:193], v[230:233], v[86:89]
	v_mfma_f32_16x16x32_bf16 v[82:85], v[206:209], v[230:233], v[82:85]
	v_mfma_f32_16x16x32_bf16 v[70:73], v[190:193], v[238:241], v[70:73]
	v_mfma_f32_16x16x32_bf16 v[66:69], v[206:209], v[238:241], v[66:69]
	v_mfma_f32_16x16x32_bf16 v[118:121], v[202:205], v[218:221], v[118:121]
	v_mfma_f32_16x16x32_bf16 v[114:117], v[210:213], v[218:221], v[114:117]
	v_mfma_f32_16x16x32_bf16 v[102:105], v[202:205], v[226:229], v[102:105]
	v_mfma_f32_16x16x32_bf16 v[98:101], v[210:213], v[226:229], v[98:101]
	v_mfma_f32_16x16x32_bf16 v[86:89], v[202:205], v[234:237], v[86:89]
	v_mfma_f32_16x16x32_bf16 v[82:85], v[210:213], v[234:237], v[82:85]
	v_mfma_f32_16x16x32_bf16 v[70:73], v[202:205], v[242:245], v[70:73]
	v_mfma_f32_16x16x32_bf16 v[66:69], v[210:213], v[242:245], v[66:69]
	s_setprio 0
	s_barrier
	s_add_i32 s6, s12, s29
	v_lshl_add_u64 v[150:151], v[150:151], 0, s[94:95]
	s_mov_b32 m0, s6
	ds_read_b128 v[214:217], v153 offset:49152
	ds_read_b128 v[218:221], v153 offset:50176
	ds_read_b128 v[222:225], v153 offset:51200
	ds_read_b128 v[226:229], v153 offset:52224
	ds_read_b128 v[230:233], v153 offset:53248
	ds_read_b128 v[234:237], v153 offset:54272
	ds_read_b128 v[238:241], v153 offset:55296
	ds_read_b128 v[242:245], v153 offset:56320
	global_load_lds_dwordx4 v[150:151], off
	s_add_i32 m0, s6, 0x2000
	s_add_u32 s6, s24, 0x18080
	v_lshl_add_u64 v[150:151], v[200:201], 0, s[94:95]
	s_addc_u32 s7, s25, 0
	s_add_i32 s12, s13, s29
	global_load_lds_dwordx4 v[150:151], off
	v_lshl_add_u64 v[150:151], s[6:7], 0, v[132:133]
	s_mov_b32 m0, s12
	s_nop 0
	global_load_lds_dwordx4 v[150:151], off
	v_lshl_add_u64 v[150:151], s[6:7], 0, v[136:137]
	s_add_i32 m0, s12, 0x2000
	s_nop 0
	global_load_lds_dwordx4 v[150:151], off
	v_lshl_add_u64 v[150:151], v[246:247], 0, s[94:95]
	s_mov_b32 m0, s46
	s_nop 0
	global_load_lds_dwordx4 v[150:151], off
	v_lshl_add_u64 v[150:151], v[248:249], 0, s[94:95]
	s_mov_b32 m0, s47
	s_nop 0
	global_load_lds_dwordx4 v[150:151], off
	s_waitcnt vmcnt(8)
	s_waitcnt lgkmcnt(0)
	s_barrier
	s_setprio 1
	s_waitcnt lgkmcnt(0)
	v_mfma_f32_16x16x32_bf16 v[62:65], v[146:149], v[214:217], v[62:65]
	v_mfma_f32_16x16x32_bf16 v[58:61], v[182:185], v[214:217], v[58:61]
	v_mfma_f32_16x16x32_bf16 v[46:49], v[146:149], v[222:225], v[46:49]
	v_mfma_f32_16x16x32_bf16 v[42:45], v[182:185], v[222:225], v[42:45]
	v_mfma_f32_16x16x32_bf16 v[30:33], v[146:149], v[230:233], v[30:33]
	v_mfma_f32_16x16x32_bf16 v[26:29], v[182:185], v[230:233], v[26:29]
	v_mfma_f32_16x16x32_bf16 v[14:17], v[146:149], v[238:241], v[14:17]
	v_mfma_f32_16x16x32_bf16 v[10:13], v[182:185], v[238:241], v[10:13]
	v_mfma_f32_16x16x32_bf16 v[62:65], v[154:157], v[218:221], v[62:65]
	v_mfma_f32_16x16x32_bf16 v[58:61], v[186:189], v[218:221], v[58:61]
	v_mfma_f32_16x16x32_bf16 v[46:49], v[154:157], v[226:229], v[46:49]
	v_mfma_f32_16x16x32_bf16 v[42:45], v[186:189], v[226:229], v[42:45]
	v_mfma_f32_16x16x32_bf16 v[30:33], v[154:157], v[234:237], v[30:33]
	v_mfma_f32_16x16x32_bf16 v[26:29], v[186:189], v[234:237], v[26:29]
	v_mfma_f32_16x16x32_bf16 v[14:17], v[154:157], v[242:245], v[14:17]
	v_mfma_f32_16x16x32_bf16 v[10:13], v[186:189], v[242:245], v[10:13]
	v_mfma_f32_16x16x32_bf16 v[54:57], v[190:193], v[214:217], v[54:57]
	v_mfma_f32_16x16x32_bf16 v[50:53], v[206:209], v[214:217], v[50:53]
	v_mfma_f32_16x16x32_bf16 v[38:41], v[190:193], v[222:225], v[38:41]
	v_mfma_f32_16x16x32_bf16 v[34:37], v[206:209], v[222:225], v[34:37]
	v_mfma_f32_16x16x32_bf16 v[22:25], v[190:193], v[230:233], v[22:25]
	v_mfma_f32_16x16x32_bf16 v[18:21], v[206:209], v[230:233], v[18:21]
	v_mfma_f32_16x16x32_bf16 v[6:9], v[190:193], v[238:241], v[6:9]
	v_mfma_f32_16x16x32_bf16 v[2:5], v[206:209], v[238:241], v[2:5]
	v_mfma_f32_16x16x32_bf16 v[54:57], v[202:205], v[218:221], v[54:57]
	v_mfma_f32_16x16x32_bf16 v[50:53], v[210:213], v[218:221], v[50:53]
	v_mfma_f32_16x16x32_bf16 v[38:41], v[202:205], v[226:229], v[38:41]
	v_mfma_f32_16x16x32_bf16 v[34:37], v[210:213], v[226:229], v[34:37]
	v_mfma_f32_16x16x32_bf16 v[22:25], v[202:205], v[234:237], v[22:25]
	v_mfma_f32_16x16x32_bf16 v[18:21], v[210:213], v[234:237], v[18:21]
	v_mfma_f32_16x16x32_bf16 v[6:9], v[202:205], v[242:245], v[6:9]
	v_mfma_f32_16x16x32_bf16 v[2:5], v[210:213], v[242:245], v[2:5]
	s_setprio 0
	s_barrier
	s_add_i32 s85, s85, 2
	s_add_u32 s76, s76, 0x100
	s_addc_u32 s84, s84, 0
	s_cmp_gt_u32 s85, 3
	s_mov_b64 s[6:7], s[8:9]
	s_cbranch_scc0 .LBB0_544
	s_and_b64 vcc, exec, s[20:21]
	s_cbranch_vccz .LBB0_547
	s_barrier

.LBB0_602:
	s_add_u32 s15, s24, s28
	s_addc_u32 s42, s25, s29
	s_add_u32 s30, s15, 0x100
	s_addc_u32 s31, s42, 0
	s_and_b64 s[12:13], s[26:27], exec
	s_cselect_b32 s31, s19, s31
	s_cselect_b32 s30, s18, s30
	s_add_u32 s12, s22, s28
	s_addc_u32 s13, s23, s29
	s_add_u32 s28, s12, 0x100
	s_addc_u32 s29, s13, 0
	s_add_i32 s75, 0, 0x10000
	s_and_b64 s[12:13], s[26:27], exec
	s_cselect_b32 s35, s17, s29
	s_cselect_b32 s34, s89, s28
	s_add_i32 s27, 0, 0x14000
	s_add_u32 s46, s15, 0x30080
	s_addc_u32 s47, s42, 0
	s_add_i32 s12, s75, s80
	s_add_i32 m0, s77, 0xc000
	s_add_i32 s81, s77, 0xe000
	s_add_i32 s78, s12, 0x2000
	v_add_u32_e32 v138, s75, v141
	s_add_u32 s42, s34, 0x10000
	ds_read_b128 v[144:147], v138
	ds_read_b128 v[148:151], v138 offset:1024
	ds_read_b128 v[152:155], v138 offset:2048
	ds_read_b128 v[182:185], v138 offset:3072
	v_add_u32_e32 v138, s27, v141
	s_addc_u32 s43, s35, 0
	s_add_i32 s13, s27, s80
	ds_read_b128 v[186:189], v138
	ds_read_b128 v[190:193], v138 offset:1024
	ds_read_b128 v[202:205], v138 offset:2048
	ds_read_b128 v[206:209], v138 offset:3072
	s_add_i32 s15, s13, 0x2000
	s_add_i32 vcc_lo, 0, 0x18000
	s_add_i32 vcc_hi, 0, 0x1c000
	s_add_u32 s28, s30, 0x30000
	s_addc_u32 s29, s31, 0
	s_add_i32 s97, vcc_lo, s80
	s_add_i32 s50, s97, 0x2000
	s_add_u32 s26, s34, 0x10080
	s_addc_u32 s27, s35, 0
	s_add_i32 s79, vcc_hi, s80
	s_add_i32 s75, s79, 0x2000
	v_lshl_add_u64 v[138:139], s[46:47], 0, v[130:131]
	ds_read_b128 v[210:213], v142
	ds_read_b128 v[214:217], v142 offset:1024
	ds_read_b128 v[218:221], v142 offset:2048
	ds_read_b128 v[222:225], v142 offset:3072
	ds_read_b128 v[226:229], v142 offset:4096
	ds_read_b128 v[230:233], v142 offset:5120
	ds_read_b128 v[234:237], v142 offset:6144
	ds_read_b128 v[238:241], v142 offset:7168
	global_load_lds_dwordx4 v[138:139], off
	v_lshl_add_u64 v[138:139], s[46:47], 0, v[134:135]
	s_mov_b32 m0, s81
	s_nop 0
	global_load_lds_dwordx4 v[138:139], off
	s_waitcnt vmcnt(8)
	s_waitcnt lgkmcnt(0)
	s_barrier
	s_setprio 1
	s_waitcnt lgkmcnt(0)
	v_mfma_f32_16x16x32_bf16 v[126:129], v[144:147], v[210:213], v[126:129]
	v_mfma_f32_16x16x32_bf16 v[122:125], v[152:155], v[210:213], v[122:125]
	v_mfma_f32_16x16x32_bf16 v[110:113], v[144:147], v[218:221], v[110:113]
	v_mfma_f32_16x16x32_bf16 v[106:109], v[152:155], v[218:221], v[106:109]
	v_mfma_f32_16x16x32_bf16 v[94:97], v[144:147], v[226:229], v[94:97]
	v_mfma_f32_16x16x32_bf16 v[90:93], v[152:155], v[226:229], v[90:93]
	v_mfma_f32_16x16x32_bf16 v[78:81], v[144:147], v[234:237], v[78:81]
	v_mfma_f32_16x16x32_bf16 v[74:77], v[152:155], v[234:237], v[74:77]
	v_mfma_f32_16x16x32_bf16 v[126:129], v[148:151], v[214:217], v[126:129]
	v_mfma_f32_16x16x32_bf16 v[122:125], v[182:185], v[214:217], v[122:125]
	v_mfma_f32_16x16x32_bf16 v[110:113], v[148:151], v[222:225], v[110:113]
	v_mfma_f32_16x16x32_bf16 v[106:109], v[182:185], v[222:225], v[106:109]
	v_mfma_f32_16x16x32_bf16 v[94:97], v[148:151], v[230:233], v[94:97]
	v_mfma_f32_16x16x32_bf16 v[90:93], v[182:185], v[230:233], v[90:93]
	v_mfma_f32_16x16x32_bf16 v[78:81], v[148:151], v[238:241], v[78:81]
	v_mfma_f32_16x16x32_bf16 v[74:77], v[182:185], v[238:241], v[74:77]
	v_mfma_f32_16x16x32_bf16 v[118:121], v[186:189], v[210:213], v[118:121]
	v_mfma_f32_16x16x32_bf16 v[114:117], v[202:205], v[210:213], v[114:117]
	v_mfma_f32_16x16x32_bf16 v[102:105], v[186:189], v[218:221], v[102:105]
	v_mfma_f32_16x16x32_bf16 v[98:101], v[202:205], v[218:221], v[98:101]
	v_mfma_f32_16x16x32_bf16 v[86:89], v[186:189], v[226:229], v[86:89]
	v_mfma_f32_16x16x32_bf16 v[82:85], v[202:205], v[226:229], v[82:85]
	v_mfma_f32_16x16x32_bf16 v[70:73], v[186:189], v[234:237], v[70:73]
	v_mfma_f32_16x16x32_bf16 v[66:69], v[202:205], v[234:237], v[66:69]
	v_mfma_f32_16x16x32_bf16 v[118:121], v[190:193], v[214:217], v[118:121]
	v_mfma_f32_16x16x32_bf16 v[114:117], v[206:209], v[214:217], v[114:117]
	v_mfma_f32_16x16x32_bf16 v[102:105], v[190:193], v[222:225], v[102:105]
	v_mfma_f32_16x16x32_bf16 v[98:101], v[206:209], v[222:225], v[98:101]
	v_mfma_f32_16x16x32_bf16 v[86:89], v[190:193], v[230:233], v[86:89]
	v_mfma_f32_16x16x32_bf16 v[82:85], v[206:209], v[230:233], v[82:85]
	v_mfma_f32_16x16x32_bf16 v[70:73], v[190:193], v[238:241], v[70:73]
	v_mfma_f32_16x16x32_bf16 v[66:69], v[206:209], v[238:241], v[66:69]
	s_setprio 0
	s_barrier
	s_mov_b32 m0, s12
	v_lshl_add_u64 v[138:139], s[34:35], 0, v[132:133]
	ds_read_b128 v[210:213], v142 offset:16384
	ds_read_b128 v[214:217], v142 offset:17408
	ds_read_b128 v[218:221], v142 offset:18432
	ds_read_b128 v[222:225], v142 offset:19456
	ds_read_b128 v[226:229], v142 offset:20480
	ds_read_b128 v[230:233], v142 offset:21504
	ds_read_b128 v[234:237], v142 offset:22528
	ds_read_b128 v[238:241], v142 offset:23552
	global_load_lds_dwordx4 v[138:139], off
	v_lshl_add_u64 v[156:157], s[34:35], 0, v[136:137]
	s_mov_b32 m0, s78
	v_lshl_add_u64 v[200:201], s[42:43], 0, v[132:133]
	global_load_lds_dwordx4 v[156:157], off
	s_mov_b32 m0, s13
	v_lshl_add_u64 v[242:243], s[30:31], 0, v[134:135]
	global_load_lds_dwordx4 v[200:201], off
	v_lshl_add_u64 v[200:201], s[42:43], 0, v[136:137]
	s_mov_b32 m0, s15
	s_nop 0
	global_load_lds_dwordx4 v[200:201], off
	v_lshl_add_u64 v[200:201], s[30:31], 0, v[130:131]
	s_mov_b32 m0, s77
	s_nop 0
	global_load_lds_dwordx4 v[200:201], off
	s_mov_b32 m0, s92
	s_nop 0
	global_load_lds_dwordx4 v[242:243], off
	s_waitcnt vmcnt(8)
	s_waitcnt lgkmcnt(0)
	s_barrier
	s_setprio 1
	s_waitcnt lgkmcnt(0)
	v_mfma_f32_16x16x32_bf16 v[62:65], v[144:147], v[210:213], v[62:65]
	v_mfma_f32_16x16x32_bf16 v[58:61], v[152:155], v[210:213], v[58:61]
	v_mfma_f32_16x16x32_bf16 v[46:49], v[144:147], v[218:221], v[46:49]
	v_mfma_f32_16x16x32_bf16 v[42:45], v[152:155], v[218:221], v[42:45]
	v_mfma_f32_16x16x32_bf16 v[30:33], v[144:147], v[226:229], v[30:33]
	v_mfma_f32_16x16x32_bf16 v[26:29], v[152:155], v[226:229], v[26:29]
	v_mfma_f32_16x16x32_bf16 v[14:17], v[144:147], v[234:237], v[14:17]
	v_mfma_f32_16x16x32_bf16 v[10:13], v[152:155], v[234:237], v[10:13]
	v_mfma_f32_16x16x32_bf16 v[62:65], v[148:151], v[214:217], v[62:65]
	v_mfma_f32_16x16x32_bf16 v[58:61], v[182:185], v[214:217], v[58:61]
	v_mfma_f32_16x16x32_bf16 v[46:49], v[148:151], v[222:225], v[46:49]
	v_mfma_f32_16x16x32_bf16 v[42:45], v[182:185], v[222:225], v[42:45]
	v_mfma_f32_16x16x32_bf16 v[30:33], v[148:151], v[230:233], v[30:33]
	v_mfma_f32_16x16x32_bf16 v[26:29], v[182:185], v[230:233], v[26:29]
	v_mfma_f32_16x16x32_bf16 v[14:17], v[148:151], v[238:241], v[14:17]
	v_mfma_f32_16x16x32_bf16 v[10:13], v[182:185], v[238:241], v[10:13]
	v_mfma_f32_16x16x32_bf16 v[54:57], v[186:189], v[210:213], v[54:57]
	v_mfma_f32_16x16x32_bf16 v[50:53], v[202:205], v[210:213], v[50:53]
	v_mfma_f32_16x16x32_bf16 v[38:41], v[186:189], v[218:221], v[38:41]
	v_mfma_f32_16x16x32_bf16 v[34:37], v[202:205], v[218:221], v[34:37]
	v_mfma_f32_16x16x32_bf16 v[22:25], v[186:189], v[226:229], v[22:25]
	v_mfma_f32_16x16x32_bf16 v[18:21], v[202:205], v[226:229], v[18:21]
	v_mfma_f32_16x16x32_bf16 v[6:9], v[186:189], v[234:237], v[6:9]
	v_mfma_f32_16x16x32_bf16 v[2:5], v[202:205], v[234:237], v[2:5]
	v_mfma_f32_16x16x32_bf16 v[54:57], v[190:193], v[214:217], v[54:57]
	v_mfma_f32_16x16x32_bf16 v[50:53], v[206:209], v[214:217], v[50:53]
	v_mfma_f32_16x16x32_bf16 v[38:41], v[190:193], v[222:225], v[38:41]
	v_mfma_f32_16x16x32_bf16 v[34:37], v[206:209], v[222:225], v[34:37]
	v_mfma_f32_16x16x32_bf16 v[22:25], v[190:193], v[230:233], v[22:25]
	v_mfma_f32_16x16x32_bf16 v[18:21], v[206:209], v[230:233], v[18:21]
	v_mfma_f32_16x16x32_bf16 v[6:9], v[190:193], v[238:241], v[6:9]
	v_mfma_f32_16x16x32_bf16 v[2:5], v[206:209], v[238:241], v[2:5]
	s_setprio 0
	s_barrier
	v_add_u32_e32 v143, vcc_lo, v141
	ds_read_b128 v[144:147], v143
	ds_read_b128 v[148:151], v143 offset:1024
	ds_read_b128 v[152:155], v143 offset:2048
	ds_read_b128 v[182:185], v143 offset:3072
	v_add_u32_e32 v143, vcc_hi, v141
	ds_read_b128 v[186:189], v143
	ds_read_b128 v[190:193], v143 offset:1024
	ds_read_b128 v[202:205], v143 offset:2048
	ds_read_b128 v[206:209], v143 offset:3072
	s_mov_b32 m0, s93
	v_lshl_add_u64 v[244:245], s[28:29], 0, v[130:131]
	ds_read_b128 v[210:213], v142 offset:32768
	ds_read_b128 v[214:217], v142 offset:33792
	ds_read_b128 v[218:221], v142 offset:34816
	ds_read_b128 v[222:225], v142 offset:35840
	ds_read_b128 v[226:229], v142 offset:36864
	ds_read_b128 v[230:233], v142 offset:37888
	ds_read_b128 v[234:237], v142 offset:38912
	ds_read_b128 v[238:241], v142 offset:39936
	global_load_lds_dwordx4 v[244:245], off
	v_lshl_add_u64 v[244:245], s[28:29], 0, v[134:135]
	s_mov_b32 m0, s96
	s_nop 0
	global_load_lds_dwordx4 v[244:245], off
	s_waitcnt vmcnt(8)
	s_waitcnt lgkmcnt(0)
	s_barrier
	s_setprio 1
	s_waitcnt lgkmcnt(0)
	v_mfma_f32_16x16x32_bf16 v[126:129], v[144:147], v[210:213], v[126:129]
	v_mfma_f32_16x16x32_bf16 v[122:125], v[152:155], v[210:213], v[122:125]
	v_mfma_f32_16x16x32_bf16 v[110:113], v[144:147], v[218:221], v[110:113]
	v_mfma_f32_16x16x32_bf16 v[106:109], v[152:155], v[218:221], v[106:109]
	v_mfma_f32_16x16x32_bf16 v[94:97], v[144:147], v[226:229], v[94:97]
	v_mfma_f32_16x16x32_bf16 v[90:93], v[152:155], v[226:229], v[90:93]
	v_mfma_f32_16x16x32_bf16 v[78:81], v[144:147], v[234:237], v[78:81]
	v_mfma_f32_16x16x32_bf16 v[74:77], v[152:155], v[234:237], v[74:77]
	v_mfma_f32_16x16x32_bf16 v[126:129], v[148:151], v[214:217], v[126:129]
	v_mfma_f32_16x16x32_bf16 v[122:125], v[182:185], v[214:217], v[122:125]
	v_mfma_f32_16x16x32_bf16 v[110:113], v[148:151], v[222:225], v[110:113]
	v_mfma_f32_16x16x32_bf16 v[106:109], v[182:185], v[222:225], v[106:109]
	v_mfma_f32_16x16x32_bf16 v[94:97], v[148:151], v[230:233], v[94:97]
	v_mfma_f32_16x16x32_bf16 v[90:93], v[182:185], v[230:233], v[90:93]
	v_mfma_f32_16x16x32_bf16 v[78:81], v[148:151], v[238:241], v[78:81]
	v_mfma_f32_16x16x32_bf16 v[74:77], v[182:185], v[238:241], v[74:77]
	v_mfma_f32_16x16x32_bf16 v[118:121], v[186:189], v[210:213], v[118:121]
	v_mfma_f32_16x16x32_bf16 v[114:117], v[202:205], v[210:213], v[114:117]
	v_mfma_f32_16x16x32_bf16 v[102:105], v[186:189], v[218:221], v[102:105]
	v_mfma_f32_16x16x32_bf16 v[98:101], v[202:205], v[218:221], v[98:101]
	v_mfma_f32_16x16x32_bf16 v[86:89], v[186:189], v[226:229], v[86:89]
	v_mfma_f32_16x16x32_bf16 v[82:85], v[202:205], v[226:229], v[82:85]
	v_mfma_f32_16x16x32_bf16 v[70:73], v[186:189], v[234:237], v[70:73]
	v_mfma_f32_16x16x32_bf16 v[66:69], v[202:205], v[234:237], v[66:69]
	v_mfma_f32_16x16x32_bf16 v[118:121], v[190:193], v[214:217], v[118:121]
	v_mfma_f32_16x16x32_bf16 v[114:117], v[206:209], v[214:217], v[114:117]
	v_mfma_f32_16x16x32_bf16 v[102:105], v[190:193], v[222:225], v[102:105]
	v_mfma_f32_16x16x32_bf16 v[98:101], v[206:209], v[222:225], v[98:101]
	v_mfma_f32_16x16x32_bf16 v[86:89], v[190:193], v[230:233], v[86:89]
	v_mfma_f32_16x16x32_bf16 v[82:85], v[206:209], v[230:233], v[82:85]
	v_mfma_f32_16x16x32_bf16 v[70:73], v[190:193], v[238:241], v[70:73]
	v_mfma_f32_16x16x32_bf16 v[66:69], v[206:209], v[238:241], v[66:69]
	s_setprio 0
	s_barrier
	s_mov_b32 m0, s97
	v_lshl_add_u64 v[138:139], v[138:139], 0, s[94:95]
	ds_read_b128 v[210:213], v142 offset:49152
	ds_read_b128 v[214:217], v142 offset:50176
	ds_read_b128 v[218:221], v142 offset:51200
	ds_read_b128 v[222:225], v142 offset:52224
	ds_read_b128 v[226:229], v142 offset:53248
	ds_read_b128 v[230:233], v142 offset:54272
	ds_read_b128 v[234:237], v142 offset:55296
	ds_read_b128 v[238:241], v142 offset:56320
	global_load_lds_dwordx4 v[138:139], off
	v_lshl_add_u64 v[138:139], v[156:157], 0, s[94:95]
	s_mov_b32 m0, s50
	s_nop 0
	global_load_lds_dwordx4 v[138:139], off
	v_lshl_add_u64 v[138:139], s[26:27], 0, v[132:133]
	s_mov_b32 m0, s79
	s_nop 0
	global_load_lds_dwordx4 v[138:139], off
	v_lshl_add_u64 v[138:139], s[26:27], 0, v[136:137]
	s_mov_b32 m0, s75
	s_nop 0
	global_load_lds_dwordx4 v[138:139], off
	v_lshl_add_u64 v[138:139], v[200:201], 0, s[94:95]
	s_mov_b32 m0, s14
	s_nop 0
	global_load_lds_dwordx4 v[138:139], off
	v_lshl_add_u64 v[138:139], v[242:243], 0, s[94:95]
	s_mov_b32 m0, s33
	s_nop 0
	global_load_lds_dwordx4 v[138:139], off
	s_waitcnt vmcnt(8)
	s_waitcnt lgkmcnt(0)
	s_barrier
	s_setprio 1
	s_waitcnt lgkmcnt(0)
	v_mfma_f32_16x16x32_bf16 v[62:65], v[144:147], v[210:213], v[62:65]
	v_mfma_f32_16x16x32_bf16 v[58:61], v[152:155], v[210:213], v[58:61]
	v_mfma_f32_16x16x32_bf16 v[46:49], v[144:147], v[218:221], v[46:49]
	v_mfma_f32_16x16x32_bf16 v[42:45], v[152:155], v[218:221], v[42:45]
	v_mfma_f32_16x16x32_bf16 v[30:33], v[144:147], v[226:229], v[30:33]
	v_mfma_f32_16x16x32_bf16 v[26:29], v[152:155], v[226:229], v[26:29]
	v_mfma_f32_16x16x32_bf16 v[14:17], v[144:147], v[234:237], v[14:17]
	v_mfma_f32_16x16x32_bf16 v[10:13], v[152:155], v[234:237], v[10:13]
	v_mfma_f32_16x16x32_bf16 v[62:65], v[148:151], v[214:217], v[62:65]
	v_mfma_f32_16x16x32_bf16 v[58:61], v[182:185], v[214:217], v[58:61]
	v_mfma_f32_16x16x32_bf16 v[46:49], v[148:151], v[222:225], v[46:49]
	v_mfma_f32_16x16x32_bf16 v[42:45], v[182:185], v[222:225], v[42:45]
	v_mfma_f32_16x16x32_bf16 v[30:33], v[148:151], v[230:233], v[30:33]
	v_mfma_f32_16x16x32_bf16 v[26:29], v[182:185], v[230:233], v[26:29]
	v_mfma_f32_16x16x32_bf16 v[14:17], v[148:151], v[238:241], v[14:17]
	v_mfma_f32_16x16x32_bf16 v[10:13], v[182:185], v[238:241], v[10:13]
	v_mfma_f32_16x16x32_bf16 v[54:57], v[186:189], v[210:213], v[54:57]
	v_mfma_f32_16x16x32_bf16 v[50:53], v[202:205], v[210:213], v[50:53]
	v_mfma_f32_16x16x32_bf16 v[38:41], v[186:189], v[218:221], v[38:41]
	v_mfma_f32_16x16x32_bf16 v[34:37], v[202:205], v[218:221], v[34:37]
	v_mfma_f32_16x16x32_bf16 v[22:25], v[186:189], v[226:229], v[22:25]
	v_mfma_f32_16x16x32_bf16 v[18:21], v[202:205], v[226:229], v[18:21]
	v_mfma_f32_16x16x32_bf16 v[6:9], v[186:189], v[234:237], v[6:9]
	v_mfma_f32_16x16x32_bf16 v[2:5], v[202:205], v[234:237], v[2:5]
	v_mfma_f32_16x16x32_bf16 v[54:57], v[190:193], v[214:217], v[54:57]
	v_mfma_f32_16x16x32_bf16 v[50:53], v[206:209], v[214:217], v[50:53]
	v_mfma_f32_16x16x32_bf16 v[38:41], v[190:193], v[222:225], v[38:41]
	v_mfma_f32_16x16x32_bf16 v[34:37], v[206:209], v[222:225], v[34:37]
	v_mfma_f32_16x16x32_bf16 v[22:25], v[190:193], v[230:233], v[22:25]
	v_mfma_f32_16x16x32_bf16 v[18:21], v[206:209], v[230:233], v[18:21]
	v_mfma_f32_16x16x32_bf16 v[6:9], v[190:193], v[238:241], v[6:9]
	v_mfma_f32_16x16x32_bf16 v[2:5], v[206:209], v[238:241], v[2:5]
	s_setprio 0
	s_barrier
	s_andn2_b64 vcc, exec, s[4:5]
	s_mov_b64 s[26:27], -1
	s_mov_b64 s[4:5], 0
	s_mov_b64 s[28:29], 0x100
	s_cbranch_vccz .LBB0_602
	s_and_b64 vcc, exec, s[10:11]
	s_cbranch_vccz .LBB0_605
	s_barrier

.LBB0_692:
	s_add_u32 s12, s42, 0xfffc0080
	s_addc_u32 s13, s43, -1
	s_add_i32 s15, 0, 0x10000
	s_cmp_eq_u32 s90, 12
	s_cselect_b32 s49, s11, s13
	s_cselect_b32 s48, s27, s12
	v_add_u32_e32 v0, s15, v188
	s_cselect_b32 s47, s25, s86
	s_cselect_b32 s46, s35, s85
	s_add_i32 s50, 0, 0x14000
	ds_read_b128 v[42:45], v0
	ds_read_b128 v[54:57], v0 offset:1024
	ds_read_b128 v[58:61], v0 offset:2048
	ds_read_b128 v[70:73], v0 offset:3072
	v_add_u32_e32 v0, s50, v188
	ds_read_b128 v[184:187], v0
	ds_read_b128 v[202:205], v0 offset:1024
	ds_read_b128 v[206:209], v0 offset:2048
	ds_read_b128 v[210:213], v0 offset:3072
	v_lshl_add_u64 v[246:247], s[42:43], 0, v[182:183]
	s_add_i32 m0, s92, 0xc000
	ds_read_b128 v[214:217], v192
	ds_read_b128 v[218:221], v192 offset:1024
	ds_read_b128 v[222:225], v192 offset:2048
	ds_read_b128 v[226:229], v192 offset:3072
	ds_read_b128 v[230:233], v192 offset:4096
	ds_read_b128 v[234:237], v192 offset:5120
	ds_read_b128 v[238:241], v192 offset:6144
	ds_read_b128 v[242:245], v192 offset:7168
	global_load_lds_dwordx4 v[246:247], off
	v_lshl_add_u64 v[246:247], s[42:43], 0, v[156:157]
	s_add_i32 m0, s92, 0xe000
	s_nop 0
	global_load_lds_dwordx4 v[246:247], off
	s_waitcnt vmcnt(8)
	s_waitcnt lgkmcnt(0)
	s_barrier
	s_setprio 1
	s_waitcnt lgkmcnt(0)
	v_mfma_f32_16x16x32_bf16 v[142:145], v[42:45], v[214:217], v[142:145]
	v_mfma_f32_16x16x32_bf16 v[138:141], v[58:61], v[214:217], v[138:141]
	v_mfma_f32_16x16x32_bf16 v[126:129], v[42:45], v[222:225], v[126:129]
	v_mfma_f32_16x16x32_bf16 v[122:125], v[58:61], v[222:225], v[122:125]
	v_mfma_f32_16x16x32_bf16 v[110:113], v[42:45], v[230:233], v[110:113]
	v_mfma_f32_16x16x32_bf16 v[106:109], v[58:61], v[230:233], v[106:109]
	v_mfma_f32_16x16x32_bf16 v[94:97], v[42:45], v[238:241], v[94:97]
	v_mfma_f32_16x16x32_bf16 v[90:93], v[58:61], v[238:241], v[90:93]
	v_mfma_f32_16x16x32_bf16 v[142:145], v[54:57], v[218:221], v[142:145]
	v_mfma_f32_16x16x32_bf16 v[138:141], v[70:73], v[218:221], v[138:141]
	v_mfma_f32_16x16x32_bf16 v[126:129], v[54:57], v[226:229], v[126:129]
	v_mfma_f32_16x16x32_bf16 v[122:125], v[70:73], v[226:229], v[122:125]
	v_mfma_f32_16x16x32_bf16 v[110:113], v[54:57], v[234:237], v[110:113]
	v_mfma_f32_16x16x32_bf16 v[106:109], v[70:73], v[234:237], v[106:109]
	v_mfma_f32_16x16x32_bf16 v[94:97], v[54:57], v[242:245], v[94:97]
	v_mfma_f32_16x16x32_bf16 v[90:93], v[70:73], v[242:245], v[90:93]
	v_mfma_f32_16x16x32_bf16 v[134:137], v[184:187], v[214:217], v[134:137]
	v_mfma_f32_16x16x32_bf16 v[130:133], v[206:209], v[214:217], v[130:133]
	v_mfma_f32_16x16x32_bf16 v[118:121], v[184:187], v[222:225], v[118:121]
	v_mfma_f32_16x16x32_bf16 v[114:117], v[206:209], v[222:225], v[114:117]
	v_mfma_f32_16x16x32_bf16 v[102:105], v[184:187], v[230:233], v[102:105]
	v_mfma_f32_16x16x32_bf16 v[98:101], v[206:209], v[230:233], v[98:101]
	v_mfma_f32_16x16x32_bf16 v[86:89], v[184:187], v[238:241], v[86:89]
	v_mfma_f32_16x16x32_bf16 v[82:85], v[206:209], v[238:241], v[82:85]
	v_mfma_f32_16x16x32_bf16 v[134:137], v[202:205], v[218:221], v[134:137]
	v_mfma_f32_16x16x32_bf16 v[130:133], v[210:213], v[218:221], v[130:133]
	v_mfma_f32_16x16x32_bf16 v[118:121], v[202:205], v[226:229], v[118:121]
	v_mfma_f32_16x16x32_bf16 v[114:117], v[210:213], v[226:229], v[114:117]
	v_mfma_f32_16x16x32_bf16 v[102:105], v[202:205], v[234:237], v[102:105]
	v_mfma_f32_16x16x32_bf16 v[98:101], v[210:213], v[234:237], v[98:101]
	v_mfma_f32_16x16x32_bf16 v[86:89], v[202:205], v[242:245], v[86:89]
	v_mfma_f32_16x16x32_bf16 v[82:85], v[210:213], v[242:245], v[82:85]
	s_setprio 0
	s_barrier
	s_add_i32 s12, s15, s81
	v_lshl_add_u64 v[246:247], s[46:47], 0, v[148:149]
	s_mov_b32 m0, s12
	ds_read_b128 v[214:217], v192 offset:16384
	ds_read_b128 v[218:221], v192 offset:17408
	ds_read_b128 v[222:225], v192 offset:18432
	ds_read_b128 v[226:229], v192 offset:19456
	ds_read_b128 v[230:233], v192 offset:20480
	ds_read_b128 v[234:237], v192 offset:21504
	ds_read_b128 v[238:241], v192 offset:22528
	ds_read_b128 v[242:245], v192 offset:23552
	global_load_lds_dwordx4 v[246:247], off
	s_add_i32 m0, s12, 0x2000
	s_add_u32 s12, s46, 0x40000
	v_lshl_add_u64 v[248:249], s[46:47], 0, v[152:153]
	s_addc_u32 s13, s47, 0
	s_add_i32 s15, s50, s81
	global_load_lds_dwordx4 v[248:249], off
	v_lshl_add_u64 v[250:251], s[12:13], 0, v[148:149]
	s_mov_b32 m0, s15
	v_lshl_add_u64 v[252:253], s[48:49], 0, v[150:151]
	global_load_lds_dwordx4 v[250:251], off
	v_lshl_add_u64 v[250:251], s[12:13], 0, v[152:153]
	s_add_i32 m0, s15, 0x2000
	s_nop 0
	global_load_lds_dwordx4 v[250:251], off
	v_lshl_add_u64 v[250:251], s[48:49], 0, v[146:147]
	s_mov_b32 m0, s92
	s_nop 0
	global_load_lds_dwordx4 v[250:251], off
	s_mov_b32 m0, s93
	s_nop 0
	global_load_lds_dwordx4 v[252:253], off
	s_waitcnt vmcnt(8)
	s_waitcnt lgkmcnt(0)
	s_barrier
	s_setprio 1
	s_waitcnt lgkmcnt(0)
	v_mfma_f32_16x16x32_bf16 v[78:81], v[42:45], v[214:217], v[78:81]
	v_mfma_f32_16x16x32_bf16 v[74:77], v[58:61], v[214:217], v[74:77]
	v_mfma_f32_16x16x32_bf16 v[50:53], v[42:45], v[222:225], v[50:53]
	v_mfma_f32_16x16x32_bf16 v[46:49], v[58:61], v[222:225], v[46:49]
	v_mfma_f32_16x16x32_bf16 v[30:33], v[42:45], v[230:233], v[30:33]
	v_mfma_f32_16x16x32_bf16 v[26:29], v[58:61], v[230:233], v[26:29]
	v_mfma_f32_16x16x32_bf16 v[14:17], v[42:45], v[238:241], v[14:17]
	v_mfma_f32_16x16x32_bf16 v[10:13], v[58:61], v[238:241], v[10:13]
	v_mfma_f32_16x16x32_bf16 v[78:81], v[54:57], v[218:221], v[78:81]
	v_mfma_f32_16x16x32_bf16 v[74:77], v[70:73], v[218:221], v[74:77]
	v_mfma_f32_16x16x32_bf16 v[50:53], v[54:57], v[226:229], v[50:53]
	v_mfma_f32_16x16x32_bf16 v[46:49], v[70:73], v[226:229], v[46:49]
	v_mfma_f32_16x16x32_bf16 v[30:33], v[54:57], v[234:237], v[30:33]
	v_mfma_f32_16x16x32_bf16 v[26:29], v[70:73], v[234:237], v[26:29]
	v_mfma_f32_16x16x32_bf16 v[14:17], v[54:57], v[242:245], v[14:17]
	v_mfma_f32_16x16x32_bf16 v[10:13], v[70:73], v[242:245], v[10:13]
	v_mfma_f32_16x16x32_bf16 v[38:41], v[184:187], v[222:225], v[38:41]
	v_mfma_f32_16x16x32_bf16 v[34:37], v[206:209], v[222:225], v[34:37]
	v_mfma_f32_16x16x32_bf16 v[22:25], v[184:187], v[230:233], v[22:25]
	v_mfma_f32_16x16x32_bf16 v[18:21], v[206:209], v[230:233], v[18:21]
	v_mfma_f32_16x16x32_bf16 v[6:9], v[184:187], v[238:241], v[6:9]
	v_mfma_f32_16x16x32_bf16 v[2:5], v[206:209], v[238:241], v[2:5]
	v_mfma_f32_16x16x32_bf16 v[42:45], v[184:187], v[214:217], v[66:69]
	v_mfma_f32_16x16x32_bf16 v[54:57], v[206:209], v[214:217], v[62:65]
	v_mfma_f32_16x16x32_bf16 v[38:41], v[202:205], v[226:229], v[38:41]
	v_mfma_f32_16x16x32_bf16 v[34:37], v[210:213], v[226:229], v[34:37]
	v_mfma_f32_16x16x32_bf16 v[22:25], v[202:205], v[234:237], v[22:25]
	v_mfma_f32_16x16x32_bf16 v[18:21], v[210:213], v[234:237], v[18:21]
	v_mfma_f32_16x16x32_bf16 v[6:9], v[202:205], v[242:245], v[6:9]
	v_mfma_f32_16x16x32_bf16 v[2:5], v[210:213], v[242:245], v[2:5]
	v_mfma_f32_16x16x32_bf16 v[42:45], v[202:205], v[218:221], v[42:45]
	v_mfma_f32_16x16x32_bf16 v[54:57], v[210:213], v[218:221], v[54:57]
	s_setprio 0
	s_barrier
	s_add_i32 s15, 0, 0x18000
	v_add_u32_e32 v0, s15, v188
	s_add_i32 s50, 0, 0x1c000
	ds_read_b128 v[58:61], v0
	ds_read_b128 v[62:65], v0 offset:1024
	ds_read_b128 v[66:69], v0 offset:2048
	ds_read_b128 v[70:73], v0 offset:3072
	v_add_u32_e32 v0, s50, v188
	ds_read_b128 v[184:187], v0
	ds_read_b128 v[202:205], v0 offset:1024
	ds_read_b128 v[206:209], v0 offset:2048
	ds_read_b128 v[210:213], v0 offset:3072
	s_add_u32 s12, s48, 0x40000
	s_addc_u32 s13, s49, 0
	s_mov_b32 m0, s96
	v_lshl_add_u64 v[200:201], s[12:13], 0, v[146:147]
	ds_read_b128 v[214:217], v192 offset:32768
	ds_read_b128 v[218:221], v192 offset:33792
	ds_read_b128 v[222:225], v192 offset:34816
	ds_read_b128 v[226:229], v192 offset:35840
	ds_read_b128 v[230:233], v192 offset:36864
	ds_read_b128 v[234:237], v192 offset:37888
	ds_read_b128 v[238:241], v192 offset:38912
	ds_read_b128 v[242:245], v192 offset:39936
	global_load_lds_dwordx4 v[200:201], off
	v_lshl_add_u64 v[200:201], s[12:13], 0, v[150:151]
	s_mov_b32 m0, s76
	s_nop 0
	global_load_lds_dwordx4 v[200:201], off
	s_waitcnt vmcnt(8)
	s_waitcnt lgkmcnt(0)
	s_barrier
	s_setprio 1
	s_waitcnt lgkmcnt(0)
	v_mfma_f32_16x16x32_bf16 v[142:145], v[58:61], v[214:217], v[142:145]
	v_mfma_f32_16x16x32_bf16 v[138:141], v[66:69], v[214:217], v[138:141]
	v_mfma_f32_16x16x32_bf16 v[126:129], v[58:61], v[222:225], v[126:129]
	v_mfma_f32_16x16x32_bf16 v[122:125], v[66:69], v[222:225], v[122:125]
	v_mfma_f32_16x16x32_bf16 v[110:113], v[58:61], v[230:233], v[110:113]
	v_mfma_f32_16x16x32_bf16 v[106:109], v[66:69], v[230:233], v[106:109]
	v_mfma_f32_16x16x32_bf16 v[94:97], v[58:61], v[238:241], v[94:97]
	v_mfma_f32_16x16x32_bf16 v[90:93], v[66:69], v[238:241], v[90:93]
	v_mfma_f32_16x16x32_bf16 v[142:145], v[62:65], v[218:221], v[142:145]
	v_mfma_f32_16x16x32_bf16 v[138:141], v[70:73], v[218:221], v[138:141]
	v_mfma_f32_16x16x32_bf16 v[126:129], v[62:65], v[226:229], v[126:129]
	v_mfma_f32_16x16x32_bf16 v[122:125], v[70:73], v[226:229], v[122:125]
	v_mfma_f32_16x16x32_bf16 v[110:113], v[62:65], v[234:237], v[110:113]
	v_mfma_f32_16x16x32_bf16 v[106:109], v[70:73], v[234:237], v[106:109]
	v_mfma_f32_16x16x32_bf16 v[94:97], v[62:65], v[242:245], v[94:97]
	v_mfma_f32_16x16x32_bf16 v[90:93], v[70:73], v[242:245], v[90:93]
	v_mfma_f32_16x16x32_bf16 v[134:137], v[184:187], v[214:217], v[134:137]
	v_mfma_f32_16x16x32_bf16 v[130:133], v[206:209], v[214:217], v[130:133]
	v_mfma_f32_16x16x32_bf16 v[118:121], v[184:187], v[222:225], v[118:121]
	v_mfma_f32_16x16x32_bf16 v[114:117], v[206:209], v[222:225], v[114:117]
	v_mfma_f32_16x16x32_bf16 v[102:105], v[184:187], v[230:233], v[102:105]
	v_mfma_f32_16x16x32_bf16 v[98:101], v[206:209], v[230:233], v[98:101]
	v_mfma_f32_16x16x32_bf16 v[86:89], v[184:187], v[238:241], v[86:89]
	v_mfma_f32_16x16x32_bf16 v[82:85], v[206:209], v[238:241], v[82:85]
	v_mfma_f32_16x16x32_bf16 v[134:137], v[202:205], v[218:221], v[134:137]
	v_mfma_f32_16x16x32_bf16 v[130:133], v[210:213], v[218:221], v[130:133]
	v_mfma_f32_16x16x32_bf16 v[118:121], v[202:205], v[226:229], v[118:121]
	v_mfma_f32_16x16x32_bf16 v[114:117], v[210:213], v[226:229], v[114:117]
	v_mfma_f32_16x16x32_bf16 v[102:105], v[202:205], v[234:237], v[102:105]
	v_mfma_f32_16x16x32_bf16 v[98:101], v[210:213], v[234:237], v[98:101]
	v_mfma_f32_16x16x32_bf16 v[86:89], v[202:205], v[242:245], v[86:89]
	v_mfma_f32_16x16x32_bf16 v[82:85], v[210:213], v[242:245], v[82:85]
	s_setprio 0
	s_barrier
	s_add_i32 s12, s15, s81
	v_lshl_add_u64 v[200:201], v[246:247], 0, s[94:95]
	s_mov_b32 m0, s12
	ds_read_b128 v[214:217], v192 offset:49152
	ds_read_b128 v[218:221], v192 offset:50176
	ds_read_b128 v[222:225], v192 offset:51200
	ds_read_b128 v[226:229], v192 offset:52224
	ds_read_b128 v[230:233], v192 offset:53248
	ds_read_b128 v[234:237], v192 offset:54272
	ds_read_b128 v[238:241], v192 offset:55296
	ds_read_b128 v[242:245], v192 offset:56320
	global_load_lds_dwordx4 v[200:201], off
	s_add_i32 m0, s12, 0x2000
	s_add_u32 s12, s46, 0x40080
	v_lshl_add_u64 v[200:201], v[248:249], 0, s[94:95]
	s_addc_u32 s13, s47, 0
	s_add_i32 s15, s50, s81
	global_load_lds_dwordx4 v[200:201], off
	v_lshl_add_u64 v[200:201], s[12:13], 0, v[148:149]
	s_mov_b32 m0, s15
	s_nop 0
	global_load_lds_dwordx4 v[200:201], off
	v_lshl_add_u64 v[200:201], s[12:13], 0, v[152:153]
	s_add_i32 m0, s15, 0x2000
	s_nop 0
	global_load_lds_dwordx4 v[200:201], off
	v_lshl_add_u64 v[200:201], v[250:251], 0, s[94:95]
	s_mov_b32 m0, s33
	s_nop 0
	global_load_lds_dwordx4 v[200:201], off
	v_lshl_add_u64 v[200:201], v[252:253], 0, s[94:95]
	s_mov_b32 m0, s89
	s_nop 0
	global_load_lds_dwordx4 v[200:201], off
	s_waitcnt vmcnt(8)
	s_waitcnt lgkmcnt(0)
	s_barrier
	s_setprio 1
	s_waitcnt lgkmcnt(0)
	v_mfma_f32_16x16x32_bf16 v[78:81], v[58:61], v[214:217], v[78:81]
	v_mfma_f32_16x16x32_bf16 v[74:77], v[66:69], v[214:217], v[74:77]
	v_mfma_f32_16x16x32_bf16 v[50:53], v[58:61], v[222:225], v[50:53]
	v_mfma_f32_16x16x32_bf16 v[46:49], v[66:69], v[222:225], v[46:49]
	v_mfma_f32_16x16x32_bf16 v[30:33], v[58:61], v[230:233], v[30:33]
	v_mfma_f32_16x16x32_bf16 v[26:29], v[66:69], v[230:233], v[26:29]
	v_mfma_f32_16x16x32_bf16 v[14:17], v[58:61], v[238:241], v[14:17]
	v_mfma_f32_16x16x32_bf16 v[10:13], v[66:69], v[238:241], v[10:13]
	v_mfma_f32_16x16x32_bf16 v[78:81], v[62:65], v[218:221], v[78:81]
	v_mfma_f32_16x16x32_bf16 v[74:77], v[70:73], v[218:221], v[74:77]
	v_mfma_f32_16x16x32_bf16 v[50:53], v[62:65], v[226:229], v[50:53]
	v_mfma_f32_16x16x32_bf16 v[46:49], v[70:73], v[226:229], v[46:49]
	v_mfma_f32_16x16x32_bf16 v[30:33], v[62:65], v[234:237], v[30:33]
	v_mfma_f32_16x16x32_bf16 v[26:29], v[70:73], v[234:237], v[26:29]
	v_mfma_f32_16x16x32_bf16 v[14:17], v[62:65], v[242:245], v[14:17]
	v_mfma_f32_16x16x32_bf16 v[10:13], v[70:73], v[242:245], v[10:13]
	v_mfma_f32_16x16x32_bf16 v[42:45], v[184:187], v[214:217], v[42:45]
	v_mfma_f32_16x16x32_bf16 v[66:69], v[202:205], v[218:221], v[42:45]
	v_mfma_f32_16x16x32_bf16 v[42:45], v[206:209], v[214:217], v[54:57]
	v_mfma_f32_16x16x32_bf16 v[38:41], v[184:187], v[222:225], v[38:41]
	v_mfma_f32_16x16x32_bf16 v[34:37], v[206:209], v[222:225], v[34:37]
	v_mfma_f32_16x16x32_bf16 v[22:25], v[184:187], v[230:233], v[22:25]
	v_mfma_f32_16x16x32_bf16 v[18:21], v[206:209], v[230:233], v[18:21]
	v_mfma_f32_16x16x32_bf16 v[6:9], v[184:187], v[238:241], v[6:9]
	v_mfma_f32_16x16x32_bf16 v[2:5], v[206:209], v[238:241], v[2:5]
	v_mfma_f32_16x16x32_bf16 v[62:65], v[210:213], v[218:221], v[42:45]
	v_mfma_f32_16x16x32_bf16 v[38:41], v[202:205], v[226:229], v[38:41]
	v_mfma_f32_16x16x32_bf16 v[34:37], v[210:213], v[226:229], v[34:37]
	v_mfma_f32_16x16x32_bf16 v[22:25], v[202:205], v[234:237], v[22:25]
	v_mfma_f32_16x16x32_bf16 v[18:21], v[210:213], v[234:237], v[18:21]
	v_mfma_f32_16x16x32_bf16 v[6:9], v[202:205], v[242:245], v[6:9]
	v_mfma_f32_16x16x32_bf16 v[2:5], v[210:213], v[242:245], v[2:5]
	s_setprio 0
	s_barrier
	s_add_i32 s90, s90, 2
	s_add_u32 s85, s85, 0x100
	s_addc_u32 s86, s86, 0
	s_add_u32 s42, s42, 0x100
	s_addc_u32 s43, s43, 0
	s_cmp_gt_u32 s90, 13
	s_cbranch_scc0 .LBB0_692
	s_and_b64 vcc, exec, s[20:21]
	s_cbranch_vccz .LBB0_695
	s_barrier

.LBB0_879:
	s_add_u32 s12, s26, 0xfffc0080
	s_addc_u32 s13, s27, -1
	s_add_i32 s15, 0, 0x10000
	s_cmp_eq_u32 s84, 12
	s_cselect_b32 s31, s14, s13
	s_cselect_b32 s30, s17, s12
	v_add_u32_e32 v0, s15, v150
	s_cselect_b32 s29, s11, s76
	s_cselect_b32 s28, s23, s33
	s_add_i32 s50, 0, 0x14000
	ds_read_b128 v[144:147], v0
	ds_read_b128 v[152:155], v0 offset:1024
	ds_read_b128 v[182:185], v0 offset:2048
	ds_read_b128 v[186:189], v0 offset:3072
	v_add_u32_e32 v0, s50, v150
	ds_read_b128 v[190:193], v0
	ds_read_b128 v[202:205], v0 offset:1024
	ds_read_b128 v[206:209], v0 offset:2048
	ds_read_b128 v[210:213], v0 offset:3072
	v_lshl_add_u64 v[148:149], s[26:27], 0, v[142:143]
	s_add_i32 m0, s25, 0xc000
	ds_read_b128 v[214:217], v151
	ds_read_b128 v[218:221], v151 offset:1024
	ds_read_b128 v[222:225], v151 offset:2048
	ds_read_b128 v[226:229], v151 offset:3072
	ds_read_b128 v[230:233], v151 offset:4096
	ds_read_b128 v[234:237], v151 offset:5120
	ds_read_b128 v[238:241], v151 offset:6144
	ds_read_b128 v[242:245], v151 offset:7168
	global_load_lds_dwordx4 v[148:149], off
	v_lshl_add_u64 v[148:149], s[26:27], 0, v[140:141]
	s_add_i32 m0, s25, 0xe000
	s_nop 0
	global_load_lds_dwordx4 v[148:149], off
	s_waitcnt vmcnt(8)
	s_waitcnt lgkmcnt(0)
	s_barrier
	s_setprio 1
	s_waitcnt lgkmcnt(0)
	v_mfma_f32_16x16x32_bf16 v[126:129], v[144:147], v[214:217], v[126:129]
	v_mfma_f32_16x16x32_bf16 v[122:125], v[182:185], v[214:217], v[122:125]
	v_mfma_f32_16x16x32_bf16 v[110:113], v[144:147], v[222:225], v[110:113]
	v_mfma_f32_16x16x32_bf16 v[106:109], v[182:185], v[222:225], v[106:109]
	v_mfma_f32_16x16x32_bf16 v[94:97], v[144:147], v[230:233], v[94:97]
	v_mfma_f32_16x16x32_bf16 v[90:93], v[182:185], v[230:233], v[90:93]
	v_mfma_f32_16x16x32_bf16 v[78:81], v[144:147], v[238:241], v[78:81]
	v_mfma_f32_16x16x32_bf16 v[74:77], v[182:185], v[238:241], v[74:77]
	v_mfma_f32_16x16x32_bf16 v[126:129], v[152:155], v[218:221], v[126:129]
	v_mfma_f32_16x16x32_bf16 v[122:125], v[186:189], v[218:221], v[122:125]
	v_mfma_f32_16x16x32_bf16 v[110:113], v[152:155], v[226:229], v[110:113]
	v_mfma_f32_16x16x32_bf16 v[106:109], v[186:189], v[226:229], v[106:109]
	v_mfma_f32_16x16x32_bf16 v[94:97], v[152:155], v[234:237], v[94:97]
	v_mfma_f32_16x16x32_bf16 v[90:93], v[186:189], v[234:237], v[90:93]
	v_mfma_f32_16x16x32_bf16 v[78:81], v[152:155], v[242:245], v[78:81]
	v_mfma_f32_16x16x32_bf16 v[74:77], v[186:189], v[242:245], v[74:77]
	v_mfma_f32_16x16x32_bf16 v[118:121], v[190:193], v[214:217], v[118:121]
	v_mfma_f32_16x16x32_bf16 v[114:117], v[206:209], v[214:217], v[114:117]
	v_mfma_f32_16x16x32_bf16 v[102:105], v[190:193], v[222:225], v[102:105]
	v_mfma_f32_16x16x32_bf16 v[98:101], v[206:209], v[222:225], v[98:101]
	v_mfma_f32_16x16x32_bf16 v[86:89], v[190:193], v[230:233], v[86:89]
	v_mfma_f32_16x16x32_bf16 v[82:85], v[206:209], v[230:233], v[82:85]
	v_mfma_f32_16x16x32_bf16 v[70:73], v[190:193], v[238:241], v[70:73]
	v_mfma_f32_16x16x32_bf16 v[66:69], v[206:209], v[238:241], v[66:69]
	v_mfma_f32_16x16x32_bf16 v[118:121], v[202:205], v[218:221], v[118:121]
	v_mfma_f32_16x16x32_bf16 v[114:117], v[210:213], v[218:221], v[114:117]
	v_mfma_f32_16x16x32_bf16 v[102:105], v[202:205], v[226:229], v[102:105]
	v_mfma_f32_16x16x32_bf16 v[98:101], v[210:213], v[226:229], v[98:101]
	v_mfma_f32_16x16x32_bf16 v[86:89], v[202:205], v[234:237], v[86:89]
	v_mfma_f32_16x16x32_bf16 v[82:85], v[210:213], v[234:237], v[82:85]
	v_mfma_f32_16x16x32_bf16 v[70:73], v[202:205], v[242:245], v[70:73]
	v_mfma_f32_16x16x32_bf16 v[66:69], v[210:213], v[242:245], v[66:69]
	s_setprio 0
	s_barrier
	s_add_i32 s12, s15, s35
	v_lshl_add_u64 v[148:149], s[28:29], 0, v[132:133]
	s_mov_b32 m0, s12
	ds_read_b128 v[214:217], v151 offset:16384
	ds_read_b128 v[218:221], v151 offset:17408
	ds_read_b128 v[222:225], v151 offset:18432
	ds_read_b128 v[226:229], v151 offset:19456
	ds_read_b128 v[230:233], v151 offset:20480
	ds_read_b128 v[234:237], v151 offset:21504
	ds_read_b128 v[238:241], v151 offset:22528
	ds_read_b128 v[242:245], v151 offset:23552
	global_load_lds_dwordx4 v[148:149], off
	s_add_i32 m0, s12, 0x2000
	s_add_u32 s12, s28, 0x40000
	v_lshl_add_u64 v[156:157], s[28:29], 0, v[136:137]
	s_addc_u32 s13, s29, 0
	s_add_i32 s15, s50, s35
	global_load_lds_dwordx4 v[156:157], off
	v_lshl_add_u64 v[200:201], s[12:13], 0, v[132:133]
	s_mov_b32 m0, s15
	v_lshl_add_u64 v[246:247], s[30:31], 0, v[134:135]
	global_load_lds_dwordx4 v[200:201], off
	v_lshl_add_u64 v[200:201], s[12:13], 0, v[136:137]
	s_add_i32 m0, s15, 0x2000
	s_nop 0
	global_load_lds_dwordx4 v[200:201], off
	v_lshl_add_u64 v[200:201], s[30:31], 0, v[130:131]
	s_mov_b32 m0, s25
	s_nop 0
	global_load_lds_dwordx4 v[200:201], off
	s_mov_b32 m0, s42
	s_nop 0
	global_load_lds_dwordx4 v[246:247], off
	s_waitcnt vmcnt(8)
	s_waitcnt lgkmcnt(0)
	s_barrier
	s_setprio 1
	s_waitcnt lgkmcnt(0)
	v_mfma_f32_16x16x32_bf16 v[62:65], v[144:147], v[214:217], v[62:65]
	v_mfma_f32_16x16x32_bf16 v[58:61], v[182:185], v[214:217], v[58:61]
	v_mfma_f32_16x16x32_bf16 v[46:49], v[144:147], v[222:225], v[46:49]
	v_mfma_f32_16x16x32_bf16 v[42:45], v[182:185], v[222:225], v[42:45]
	v_mfma_f32_16x16x32_bf16 v[30:33], v[144:147], v[230:233], v[30:33]
	v_mfma_f32_16x16x32_bf16 v[26:29], v[182:185], v[230:233], v[26:29]
	v_mfma_f32_16x16x32_bf16 v[14:17], v[144:147], v[238:241], v[14:17]
	v_mfma_f32_16x16x32_bf16 v[10:13], v[182:185], v[238:241], v[10:13]
	v_mfma_f32_16x16x32_bf16 v[62:65], v[152:155], v[218:221], v[62:65]
	v_mfma_f32_16x16x32_bf16 v[58:61], v[186:189], v[218:221], v[58:61]
	v_mfma_f32_16x16x32_bf16 v[46:49], v[152:155], v[226:229], v[46:49]
	v_mfma_f32_16x16x32_bf16 v[42:45], v[186:189], v[226:229], v[42:45]
	v_mfma_f32_16x16x32_bf16 v[30:33], v[152:155], v[234:237], v[30:33]
	v_mfma_f32_16x16x32_bf16 v[26:29], v[186:189], v[234:237], v[26:29]
	v_mfma_f32_16x16x32_bf16 v[14:17], v[152:155], v[242:245], v[14:17]
	v_mfma_f32_16x16x32_bf16 v[10:13], v[186:189], v[242:245], v[10:13]
	v_mfma_f32_16x16x32_bf16 v[54:57], v[190:193], v[214:217], v[54:57]
	v_mfma_f32_16x16x32_bf16 v[50:53], v[206:209], v[214:217], v[50:53]
	v_mfma_f32_16x16x32_bf16 v[38:41], v[190:193], v[222:225], v[38:41]
	v_mfma_f32_16x16x32_bf16 v[34:37], v[206:209], v[222:225], v[34:37]
	v_mfma_f32_16x16x32_bf16 v[22:25], v[190:193], v[230:233], v[22:25]
	v_mfma_f32_16x16x32_bf16 v[18:21], v[206:209], v[230:233], v[18:21]
	v_mfma_f32_16x16x32_bf16 v[6:9], v[190:193], v[238:241], v[6:9]
	v_mfma_f32_16x16x32_bf16 v[2:5], v[206:209], v[238:241], v[2:5]
	v_mfma_f32_16x16x32_bf16 v[54:57], v[202:205], v[218:221], v[54:57]
	v_mfma_f32_16x16x32_bf16 v[50:53], v[210:213], v[218:221], v[50:53]
	v_mfma_f32_16x16x32_bf16 v[38:41], v[202:205], v[226:229], v[38:41]
	v_mfma_f32_16x16x32_bf16 v[34:37], v[210:213], v[226:229], v[34:37]
	v_mfma_f32_16x16x32_bf16 v[22:25], v[202:205], v[234:237], v[22:25]
	v_mfma_f32_16x16x32_bf16 v[18:21], v[210:213], v[234:237], v[18:21]
	v_mfma_f32_16x16x32_bf16 v[6:9], v[202:205], v[242:245], v[6:9]
	v_mfma_f32_16x16x32_bf16 v[2:5], v[210:213], v[242:245], v[2:5]
	s_setprio 0
	s_barrier
	s_add_i32 s15, 0, 0x18000
	v_add_u32_e32 v0, s15, v150
	s_add_i32 s50, 0, 0x1c000
	ds_read_b128 v[144:147], v0
	ds_read_b128 v[152:155], v0 offset:1024
	ds_read_b128 v[182:185], v0 offset:2048
	ds_read_b128 v[186:189], v0 offset:3072
	v_add_u32_e32 v0, s50, v150
	ds_read_b128 v[190:193], v0
	ds_read_b128 v[202:205], v0 offset:1024
	ds_read_b128 v[206:209], v0 offset:2048
	ds_read_b128 v[210:213], v0 offset:3072
	s_add_u32 s12, s30, 0x40000
	s_addc_u32 s13, s31, 0
	s_mov_b32 m0, s43
	v_lshl_add_u64 v[248:249], s[12:13], 0, v[130:131]
	ds_read_b128 v[214:217], v151 offset:32768
	ds_read_b128 v[218:221], v151 offset:33792
	ds_read_b128 v[222:225], v151 offset:34816
	ds_read_b128 v[226:229], v151 offset:35840
	ds_read_b128 v[230:233], v151 offset:36864
	ds_read_b128 v[234:237], v151 offset:37888
	ds_read_b128 v[238:241], v151 offset:38912
	ds_read_b128 v[242:245], v151 offset:39936
	global_load_lds_dwordx4 v[248:249], off
	v_lshl_add_u64 v[248:249], s[12:13], 0, v[134:135]
	s_mov_b32 m0, s46
	s_nop 0
	global_load_lds_dwordx4 v[248:249], off
	s_waitcnt vmcnt(8)
	s_waitcnt lgkmcnt(0)
	s_barrier
	s_setprio 1
	s_waitcnt lgkmcnt(0)
	v_mfma_f32_16x16x32_bf16 v[126:129], v[144:147], v[214:217], v[126:129]
	v_mfma_f32_16x16x32_bf16 v[122:125], v[182:185], v[214:217], v[122:125]
	v_mfma_f32_16x16x32_bf16 v[110:113], v[144:147], v[222:225], v[110:113]
	v_mfma_f32_16x16x32_bf16 v[106:109], v[182:185], v[222:225], v[106:109]
	v_mfma_f32_16x16x32_bf16 v[94:97], v[144:147], v[230:233], v[94:97]
	v_mfma_f32_16x16x32_bf16 v[90:93], v[182:185], v[230:233], v[90:93]
	v_mfma_f32_16x16x32_bf16 v[78:81], v[144:147], v[238:241], v[78:81]
	v_mfma_f32_16x16x32_bf16 v[74:77], v[182:185], v[238:241], v[74:77]
	v_mfma_f32_16x16x32_bf16 v[126:129], v[152:155], v[218:221], v[126:129]
	v_mfma_f32_16x16x32_bf16 v[122:125], v[186:189], v[218:221], v[122:125]
	v_mfma_f32_16x16x32_bf16 v[110:113], v[152:155], v[226:229], v[110:113]
	v_mfma_f32_16x16x32_bf16 v[106:109], v[186:189], v[226:229], v[106:109]
	v_mfma_f32_16x16x32_bf16 v[94:97], v[152:155], v[234:237], v[94:97]
	v_mfma_f32_16x16x32_bf16 v[90:93], v[186:189], v[234:237], v[90:93]
	v_mfma_f32_16x16x32_bf16 v[78:81], v[152:155], v[242:245], v[78:81]
	v_mfma_f32_16x16x32_bf16 v[74:77], v[186:189], v[242:245], v[74:77]
	v_mfma_f32_16x16x32_bf16 v[118:121], v[190:193], v[214:217], v[118:121]
	v_mfma_f32_16x16x32_bf16 v[114:117], v[206:209], v[214:217], v[114:117]
	v_mfma_f32_16x16x32_bf16 v[102:105], v[190:193], v[222:225], v[102:105]
	v_mfma_f32_16x16x32_bf16 v[98:101], v[206:209], v[222:225], v[98:101]
	v_mfma_f32_16x16x32_bf16 v[86:89], v[190:193], v[230:233], v[86:89]
	v_mfma_f32_16x16x32_bf16 v[82:85], v[206:209], v[230:233], v[82:85]
	v_mfma_f32_16x16x32_bf16 v[70:73], v[190:193], v[238:241], v[70:73]
	v_mfma_f32_16x16x32_bf16 v[66:69], v[206:209], v[238:241], v[66:69]
	v_mfma_f32_16x16x32_bf16 v[118:121], v[202:205], v[218:221], v[118:121]
	v_mfma_f32_16x16x32_bf16 v[114:117], v[210:213], v[218:221], v[114:117]
	v_mfma_f32_16x16x32_bf16 v[102:105], v[202:205], v[226:229], v[102:105]
	v_mfma_f32_16x16x32_bf16 v[98:101], v[210:213], v[226:229], v[98:101]
	v_mfma_f32_16x16x32_bf16 v[86:89], v[202:205], v[234:237], v[86:89]
	v_mfma_f32_16x16x32_bf16 v[82:85], v[210:213], v[234:237], v[82:85]
	v_mfma_f32_16x16x32_bf16 v[70:73], v[202:205], v[242:245], v[70:73]
	v_mfma_f32_16x16x32_bf16 v[66:69], v[210:213], v[242:245], v[66:69]
	s_setprio 0
	s_barrier
	s_add_i32 s12, s15, s35
	v_lshl_add_u64 v[148:149], v[148:149], 0, s[94:95]
	s_mov_b32 m0, s12
	ds_read_b128 v[214:217], v151 offset:49152
	ds_read_b128 v[218:221], v151 offset:50176
	ds_read_b128 v[222:225], v151 offset:51200
	ds_read_b128 v[226:229], v151 offset:52224
	ds_read_b128 v[230:233], v151 offset:53248
	ds_read_b128 v[234:237], v151 offset:54272
	ds_read_b128 v[238:241], v151 offset:55296
	ds_read_b128 v[242:245], v151 offset:56320
	global_load_lds_dwordx4 v[148:149], off
	s_add_i32 m0, s12, 0x2000
	s_add_u32 s12, s28, 0x40080
	v_lshl_add_u64 v[148:149], v[156:157], 0, s[94:95]
	s_addc_u32 s13, s29, 0
	s_add_i32 s15, s50, s35
	global_load_lds_dwordx4 v[148:149], off
	v_lshl_add_u64 v[148:149], s[12:13], 0, v[132:133]
	s_mov_b32 m0, s15
	s_nop 0
	global_load_lds_dwordx4 v[148:149], off
	v_lshl_add_u64 v[148:149], s[12:13], 0, v[136:137]
	s_add_i32 m0, s15, 0x2000
	s_nop 0
	global_load_lds_dwordx4 v[148:149], off
	v_lshl_add_u64 v[148:149], v[200:201], 0, s[94:95]
	s_mov_b32 m0, s47
	s_nop 0
	global_load_lds_dwordx4 v[148:149], off
	v_lshl_add_u64 v[148:149], v[246:247], 0, s[94:95]
	s_mov_b32 m0, s48
	s_nop 0
	global_load_lds_dwordx4 v[148:149], off
	s_waitcnt vmcnt(8)
	s_waitcnt lgkmcnt(0)
	s_barrier
	s_setprio 1
	s_waitcnt lgkmcnt(0)
	v_mfma_f32_16x16x32_bf16 v[62:65], v[144:147], v[214:217], v[62:65]
	v_mfma_f32_16x16x32_bf16 v[58:61], v[182:185], v[214:217], v[58:61]
	v_mfma_f32_16x16x32_bf16 v[46:49], v[144:147], v[222:225], v[46:49]
	v_mfma_f32_16x16x32_bf16 v[42:45], v[182:185], v[222:225], v[42:45]
	v_mfma_f32_16x16x32_bf16 v[30:33], v[144:147], v[230:233], v[30:33]
	v_mfma_f32_16x16x32_bf16 v[26:29], v[182:185], v[230:233], v[26:29]
	v_mfma_f32_16x16x32_bf16 v[14:17], v[144:147], v[238:241], v[14:17]
	v_mfma_f32_16x16x32_bf16 v[10:13], v[182:185], v[238:241], v[10:13]
	v_mfma_f32_16x16x32_bf16 v[62:65], v[152:155], v[218:221], v[62:65]
	v_mfma_f32_16x16x32_bf16 v[58:61], v[186:189], v[218:221], v[58:61]
	v_mfma_f32_16x16x32_bf16 v[46:49], v[152:155], v[226:229], v[46:49]
	v_mfma_f32_16x16x32_bf16 v[42:45], v[186:189], v[226:229], v[42:45]
	v_mfma_f32_16x16x32_bf16 v[30:33], v[152:155], v[234:237], v[30:33]
	v_mfma_f32_16x16x32_bf16 v[26:29], v[186:189], v[234:237], v[26:29]
	v_mfma_f32_16x16x32_bf16 v[14:17], v[152:155], v[242:245], v[14:17]
	v_mfma_f32_16x16x32_bf16 v[10:13], v[186:189], v[242:245], v[10:13]
	v_mfma_f32_16x16x32_bf16 v[54:57], v[190:193], v[214:217], v[54:57]
	v_mfma_f32_16x16x32_bf16 v[50:53], v[206:209], v[214:217], v[50:53]
	v_mfma_f32_16x16x32_bf16 v[38:41], v[190:193], v[222:225], v[38:41]
	v_mfma_f32_16x16x32_bf16 v[34:37], v[206:209], v[222:225], v[34:37]
	v_mfma_f32_16x16x32_bf16 v[22:25], v[190:193], v[230:233], v[22:25]
	v_mfma_f32_16x16x32_bf16 v[18:21], v[206:209], v[230:233], v[18:21]
	v_mfma_f32_16x16x32_bf16 v[6:9], v[190:193], v[238:241], v[6:9]
	v_mfma_f32_16x16x32_bf16 v[2:5], v[206:209], v[238:241], v[2:5]
	v_mfma_f32_16x16x32_bf16 v[54:57], v[202:205], v[218:221], v[54:57]
	v_mfma_f32_16x16x32_bf16 v[50:53], v[210:213], v[218:221], v[50:53]
	v_mfma_f32_16x16x32_bf16 v[38:41], v[202:205], v[226:229], v[38:41]
	v_mfma_f32_16x16x32_bf16 v[34:37], v[210:213], v[226:229], v[34:37]
	v_mfma_f32_16x16x32_bf16 v[22:25], v[202:205], v[234:237], v[22:25]
	v_mfma_f32_16x16x32_bf16 v[18:21], v[210:213], v[234:237], v[18:21]
	v_mfma_f32_16x16x32_bf16 v[6:9], v[202:205], v[242:245], v[6:9]
	v_mfma_f32_16x16x32_bf16 v[2:5], v[210:213], v[242:245], v[2:5]
	s_setprio 0
	s_barrier
	s_add_i32 s84, s84, 2
	s_add_u32 s33, s33, 0x100
	s_addc_u32 s76, s76, 0
	s_add_u32 s26, s26, 0x100
	s_addc_u32 s27, s27, 0
	s_cmp_gt_u32 s84, 13
	s_cbranch_scc0 .LBB0_879
	s_and_b64 vcc, exec, s[8:9]
	s_cbranch_vccz .LBB0_882
	s_barrier

.LBB0_955:
	s_add_u32 s12, s24, 0xfffc0080
	s_addc_u32 s13, s25, -1
	s_add_i32 s15, 0, 0x10000
	s_cmp_eq_u32 s85, 12
	s_cselect_b32 s29, s17, s13
	s_cselect_b32 s28, s23, s12
	v_add_u32_e32 v142, s15, v145
	s_cselect_b32 s27, s11, s84
	s_cselect_b32 s26, s33, s76
	s_add_i32 s50, 0, 0x14000
	ds_read_b128 v[148:151], v142
	ds_read_b128 v[152:155], v142 offset:1024
	ds_read_b128 v[182:185], v142 offset:2048
	ds_read_b128 v[186:189], v142 offset:3072
	v_add_u32_e32 v142, s50, v145
	ds_read_b128 v[190:193], v142
	ds_read_b128 v[202:205], v142 offset:1024
	ds_read_b128 v[206:209], v142 offset:2048
	ds_read_b128 v[210:213], v142 offset:3072
	v_lshl_add_u64 v[142:143], s[24:25], 0, v[140:141]
	s_add_i32 m0, s35, 0xc000
	ds_read_b128 v[214:217], v146
	ds_read_b128 v[218:221], v146 offset:1024
	ds_read_b128 v[222:225], v146 offset:2048
	ds_read_b128 v[226:229], v146 offset:3072
	ds_read_b128 v[230:233], v146 offset:4096
	ds_read_b128 v[234:237], v146 offset:5120
	ds_read_b128 v[238:241], v146 offset:6144
	ds_read_b128 v[242:245], v146 offset:7168
	global_load_lds_dwordx4 v[142:143], off
	v_lshl_add_u64 v[142:143], s[24:25], 0, v[138:139]
	s_add_i32 m0, s35, 0xe000
	s_nop 0
	global_load_lds_dwordx4 v[142:143], off
	s_waitcnt vmcnt(8)
	s_waitcnt lgkmcnt(0)
	s_barrier
	s_setprio 1
	s_waitcnt lgkmcnt(0)
	v_mfma_f32_16x16x32_bf16 v[126:129], v[148:151], v[214:217], v[126:129]
	v_mfma_f32_16x16x32_bf16 v[122:125], v[182:185], v[214:217], v[122:125]
	v_mfma_f32_16x16x32_bf16 v[110:113], v[148:151], v[222:225], v[110:113]
	v_mfma_f32_16x16x32_bf16 v[106:109], v[182:185], v[222:225], v[106:109]
	v_mfma_f32_16x16x32_bf16 v[94:97], v[148:151], v[230:233], v[94:97]
	v_mfma_f32_16x16x32_bf16 v[90:93], v[182:185], v[230:233], v[90:93]
	v_mfma_f32_16x16x32_bf16 v[78:81], v[148:151], v[238:241], v[78:81]
	v_mfma_f32_16x16x32_bf16 v[74:77], v[182:185], v[238:241], v[74:77]
	v_mfma_f32_16x16x32_bf16 v[126:129], v[152:155], v[218:221], v[126:129]
	v_mfma_f32_16x16x32_bf16 v[122:125], v[186:189], v[218:221], v[122:125]
	v_mfma_f32_16x16x32_bf16 v[110:113], v[152:155], v[226:229], v[110:113]
	v_mfma_f32_16x16x32_bf16 v[106:109], v[186:189], v[226:229], v[106:109]
	v_mfma_f32_16x16x32_bf16 v[94:97], v[152:155], v[234:237], v[94:97]
	v_mfma_f32_16x16x32_bf16 v[90:93], v[186:189], v[234:237], v[90:93]
	v_mfma_f32_16x16x32_bf16 v[78:81], v[152:155], v[242:245], v[78:81]
	v_mfma_f32_16x16x32_bf16 v[74:77], v[186:189], v[242:245], v[74:77]
	v_mfma_f32_16x16x32_bf16 v[118:121], v[190:193], v[214:217], v[118:121]
	v_mfma_f32_16x16x32_bf16 v[114:117], v[206:209], v[214:217], v[114:117]
	v_mfma_f32_16x16x32_bf16 v[102:105], v[190:193], v[222:225], v[102:105]
	v_mfma_f32_16x16x32_bf16 v[98:101], v[206:209], v[222:225], v[98:101]
	v_mfma_f32_16x16x32_bf16 v[86:89], v[190:193], v[230:233], v[86:89]
	v_mfma_f32_16x16x32_bf16 v[82:85], v[206:209], v[230:233], v[82:85]
	v_mfma_f32_16x16x32_bf16 v[70:73], v[190:193], v[238:241], v[70:73]
	v_mfma_f32_16x16x32_bf16 v[66:69], v[206:209], v[238:241], v[66:69]
	v_mfma_f32_16x16x32_bf16 v[118:121], v[202:205], v[218:221], v[118:121]
	v_mfma_f32_16x16x32_bf16 v[114:117], v[210:213], v[218:221], v[114:117]
	v_mfma_f32_16x16x32_bf16 v[102:105], v[202:205], v[226:229], v[102:105]
	v_mfma_f32_16x16x32_bf16 v[98:101], v[210:213], v[226:229], v[98:101]
	v_mfma_f32_16x16x32_bf16 v[86:89], v[202:205], v[234:237], v[86:89]
	v_mfma_f32_16x16x32_bf16 v[82:85], v[210:213], v[234:237], v[82:85]
	v_mfma_f32_16x16x32_bf16 v[70:73], v[202:205], v[242:245], v[70:73]
	v_mfma_f32_16x16x32_bf16 v[66:69], v[210:213], v[242:245], v[66:69]
	s_setprio 0
	s_barrier
	s_add_i32 s12, s15, s31
	v_lshl_add_u64 v[142:143], s[26:27], 0, v[134:135]
	s_mov_b32 m0, s12
	ds_read_b128 v[214:217], v146 offset:16384
	ds_read_b128 v[218:221], v146 offset:17408
	ds_read_b128 v[222:225], v146 offset:18432
	ds_read_b128 v[226:229], v146 offset:19456
	ds_read_b128 v[230:233], v146 offset:20480
	ds_read_b128 v[234:237], v146 offset:21504
	ds_read_b128 v[238:241], v146 offset:22528
	ds_read_b128 v[242:245], v146 offset:23552
	global_load_lds_dwordx4 v[142:143], off
	s_add_i32 m0, s12, 0x2000
	s_add_u32 s12, s26, 0x40000
	v_lshl_add_u64 v[156:157], s[26:27], 0, v[130:131]
	s_addc_u32 s13, s27, 0
	s_add_i32 s15, s50, s31
	global_load_lds_dwordx4 v[156:157], off
	v_lshl_add_u64 v[200:201], s[12:13], 0, v[134:135]
	s_mov_b32 m0, s15
	v_lshl_add_u64 v[246:247], s[28:29], 0, v[132:133]
	global_load_lds_dwordx4 v[200:201], off
	v_lshl_add_u64 v[200:201], s[12:13], 0, v[130:131]
	s_add_i32 m0, s15, 0x2000
	s_nop 0
	global_load_lds_dwordx4 v[200:201], off
	v_lshl_add_u64 v[200:201], s[28:29], 0, v[136:137]
	s_mov_b32 m0, s35
	s_nop 0
	global_load_lds_dwordx4 v[200:201], off
	s_mov_b32 m0, s42
	s_nop 0
	global_load_lds_dwordx4 v[246:247], off
	s_waitcnt vmcnt(8)
	s_waitcnt lgkmcnt(0)
	s_barrier
	s_setprio 1
	s_waitcnt lgkmcnt(0)
	v_mfma_f32_16x16x32_bf16 v[62:65], v[148:151], v[214:217], v[62:65]
	v_mfma_f32_16x16x32_bf16 v[58:61], v[182:185], v[214:217], v[58:61]
	v_mfma_f32_16x16x32_bf16 v[46:49], v[148:151], v[222:225], v[46:49]
	v_mfma_f32_16x16x32_bf16 v[42:45], v[182:185], v[222:225], v[42:45]
	v_mfma_f32_16x16x32_bf16 v[30:33], v[148:151], v[230:233], v[30:33]
	v_mfma_f32_16x16x32_bf16 v[26:29], v[182:185], v[230:233], v[26:29]
	v_mfma_f32_16x16x32_bf16 v[14:17], v[148:151], v[238:241], v[14:17]
	v_mfma_f32_16x16x32_bf16 v[10:13], v[182:185], v[238:241], v[10:13]
	v_mfma_f32_16x16x32_bf16 v[62:65], v[152:155], v[218:221], v[62:65]
	v_mfma_f32_16x16x32_bf16 v[58:61], v[186:189], v[218:221], v[58:61]
	v_mfma_f32_16x16x32_bf16 v[46:49], v[152:155], v[226:229], v[46:49]
	v_mfma_f32_16x16x32_bf16 v[42:45], v[186:189], v[226:229], v[42:45]
	v_mfma_f32_16x16x32_bf16 v[30:33], v[152:155], v[234:237], v[30:33]
	v_mfma_f32_16x16x32_bf16 v[26:29], v[186:189], v[234:237], v[26:29]
	v_mfma_f32_16x16x32_bf16 v[14:17], v[152:155], v[242:245], v[14:17]
	v_mfma_f32_16x16x32_bf16 v[10:13], v[186:189], v[242:245], v[10:13]
	v_mfma_f32_16x16x32_bf16 v[54:57], v[190:193], v[214:217], v[54:57]
	v_mfma_f32_16x16x32_bf16 v[50:53], v[206:209], v[214:217], v[50:53]
	v_mfma_f32_16x16x32_bf16 v[38:41], v[190:193], v[222:225], v[38:41]
	v_mfma_f32_16x16x32_bf16 v[34:37], v[206:209], v[222:225], v[34:37]
	v_mfma_f32_16x16x32_bf16 v[22:25], v[190:193], v[230:233], v[22:25]
	v_mfma_f32_16x16x32_bf16 v[18:21], v[206:209], v[230:233], v[18:21]
	v_mfma_f32_16x16x32_bf16 v[6:9], v[190:193], v[238:241], v[6:9]
	v_mfma_f32_16x16x32_bf16 v[2:5], v[206:209], v[238:241], v[2:5]
	v_mfma_f32_16x16x32_bf16 v[54:57], v[202:205], v[218:221], v[54:57]
	v_mfma_f32_16x16x32_bf16 v[50:53], v[210:213], v[218:221], v[50:53]
	v_mfma_f32_16x16x32_bf16 v[38:41], v[202:205], v[226:229], v[38:41]
	v_mfma_f32_16x16x32_bf16 v[34:37], v[210:213], v[226:229], v[34:37]
	v_mfma_f32_16x16x32_bf16 v[22:25], v[202:205], v[234:237], v[22:25]
	v_mfma_f32_16x16x32_bf16 v[18:21], v[210:213], v[234:237], v[18:21]
	v_mfma_f32_16x16x32_bf16 v[6:9], v[202:205], v[242:245], v[6:9]
	v_mfma_f32_16x16x32_bf16 v[2:5], v[210:213], v[242:245], v[2:5]
	s_setprio 0
	s_barrier
	s_add_i32 s15, 0, 0x18000
	v_add_u32_e32 v147, s15, v145
	s_add_i32 s50, 0, 0x1c000
	ds_read_b128 v[148:151], v147
	ds_read_b128 v[152:155], v147 offset:1024
	ds_read_b128 v[182:185], v147 offset:2048
	ds_read_b128 v[186:189], v147 offset:3072
	v_add_u32_e32 v147, s50, v145
	ds_read_b128 v[190:193], v147
	ds_read_b128 v[202:205], v147 offset:1024
	ds_read_b128 v[206:209], v147 offset:2048
	ds_read_b128 v[210:213], v147 offset:3072
	s_add_u32 s12, s28, 0x40000
	s_addc_u32 s13, s29, 0
	s_mov_b32 m0, s43
	v_lshl_add_u64 v[248:249], s[12:13], 0, v[136:137]
	ds_read_b128 v[214:217], v146 offset:32768
	ds_read_b128 v[218:221], v146 offset:33792
	ds_read_b128 v[222:225], v146 offset:34816
	ds_read_b128 v[226:229], v146 offset:35840
	ds_read_b128 v[230:233], v146 offset:36864
	ds_read_b128 v[234:237], v146 offset:37888
	ds_read_b128 v[238:241], v146 offset:38912
	ds_read_b128 v[242:245], v146 offset:39936
	global_load_lds_dwordx4 v[248:249], off
	v_lshl_add_u64 v[248:249], s[12:13], 0, v[132:133]
	s_mov_b32 m0, s46
	s_nop 0
	global_load_lds_dwordx4 v[248:249], off
	s_waitcnt vmcnt(8)
	s_waitcnt lgkmcnt(0)
	s_barrier
	s_setprio 1
	s_waitcnt lgkmcnt(0)
	v_mfma_f32_16x16x32_bf16 v[126:129], v[148:151], v[214:217], v[126:129]
	v_mfma_f32_16x16x32_bf16 v[122:125], v[182:185], v[214:217], v[122:125]
	v_mfma_f32_16x16x32_bf16 v[110:113], v[148:151], v[222:225], v[110:113]
	v_mfma_f32_16x16x32_bf16 v[106:109], v[182:185], v[222:225], v[106:109]
	v_mfma_f32_16x16x32_bf16 v[94:97], v[148:151], v[230:233], v[94:97]
	v_mfma_f32_16x16x32_bf16 v[90:93], v[182:185], v[230:233], v[90:93]
	v_mfma_f32_16x16x32_bf16 v[78:81], v[148:151], v[238:241], v[78:81]
	v_mfma_f32_16x16x32_bf16 v[74:77], v[182:185], v[238:241], v[74:77]
	v_mfma_f32_16x16x32_bf16 v[126:129], v[152:155], v[218:221], v[126:129]
	v_mfma_f32_16x16x32_bf16 v[122:125], v[186:189], v[218:221], v[122:125]
	v_mfma_f32_16x16x32_bf16 v[110:113], v[152:155], v[226:229], v[110:113]
	v_mfma_f32_16x16x32_bf16 v[106:109], v[186:189], v[226:229], v[106:109]
	v_mfma_f32_16x16x32_bf16 v[94:97], v[152:155], v[234:237], v[94:97]
	v_mfma_f32_16x16x32_bf16 v[90:93], v[186:189], v[234:237], v[90:93]
	v_mfma_f32_16x16x32_bf16 v[78:81], v[152:155], v[242:245], v[78:81]
	v_mfma_f32_16x16x32_bf16 v[74:77], v[186:189], v[242:245], v[74:77]
	v_mfma_f32_16x16x32_bf16 v[118:121], v[190:193], v[214:217], v[118:121]
	v_mfma_f32_16x16x32_bf16 v[114:117], v[206:209], v[214:217], v[114:117]
	v_mfma_f32_16x16x32_bf16 v[102:105], v[190:193], v[222:225], v[102:105]
	v_mfma_f32_16x16x32_bf16 v[98:101], v[206:209], v[222:225], v[98:101]
	v_mfma_f32_16x16x32_bf16 v[86:89], v[190:193], v[230:233], v[86:89]
	v_mfma_f32_16x16x32_bf16 v[82:85], v[206:209], v[230:233], v[82:85]
	v_mfma_f32_16x16x32_bf16 v[70:73], v[190:193], v[238:241], v[70:73]
	v_mfma_f32_16x16x32_bf16 v[66:69], v[206:209], v[238:241], v[66:69]
	v_mfma_f32_16x16x32_bf16 v[118:121], v[202:205], v[218:221], v[118:121]
	v_mfma_f32_16x16x32_bf16 v[114:117], v[210:213], v[218:221], v[114:117]
	v_mfma_f32_16x16x32_bf16 v[102:105], v[202:205], v[226:229], v[102:105]
	v_mfma_f32_16x16x32_bf16 v[98:101], v[210:213], v[226:229], v[98:101]
	v_mfma_f32_16x16x32_bf16 v[86:89], v[202:205], v[234:237], v[86:89]
	v_mfma_f32_16x16x32_bf16 v[82:85], v[210:213], v[234:237], v[82:85]
	v_mfma_f32_16x16x32_bf16 v[70:73], v[202:205], v[242:245], v[70:73]
	v_mfma_f32_16x16x32_bf16 v[66:69], v[210:213], v[242:245], v[66:69]
	s_setprio 0
	s_barrier
	s_add_i32 s12, s15, s31
	v_lshl_add_u64 v[142:143], v[142:143], 0, s[94:95]
	s_mov_b32 m0, s12
	ds_read_b128 v[214:217], v146 offset:49152
	ds_read_b128 v[218:221], v146 offset:50176
	ds_read_b128 v[222:225], v146 offset:51200
	ds_read_b128 v[226:229], v146 offset:52224
	ds_read_b128 v[230:233], v146 offset:53248
	ds_read_b128 v[234:237], v146 offset:54272
	ds_read_b128 v[238:241], v146 offset:55296
	ds_read_b128 v[242:245], v146 offset:56320
	global_load_lds_dwordx4 v[142:143], off
	s_add_i32 m0, s12, 0x2000
	s_add_u32 s12, s26, 0x40080
	v_lshl_add_u64 v[142:143], v[156:157], 0, s[94:95]
	s_addc_u32 s13, s27, 0
	s_add_i32 s15, s50, s31
	global_load_lds_dwordx4 v[142:143], off
	v_lshl_add_u64 v[142:143], s[12:13], 0, v[134:135]
	s_mov_b32 m0, s15
	s_nop 0
	global_load_lds_dwordx4 v[142:143], off
	v_lshl_add_u64 v[142:143], s[12:13], 0, v[130:131]
	s_add_i32 m0, s15, 0x2000
	s_nop 0
	global_load_lds_dwordx4 v[142:143], off
	v_lshl_add_u64 v[142:143], v[200:201], 0, s[94:95]
	s_mov_b32 m0, s47
	s_nop 0
	global_load_lds_dwordx4 v[142:143], off
	v_lshl_add_u64 v[142:143], v[246:247], 0, s[94:95]
	s_mov_b32 m0, s48
	s_nop 0
	global_load_lds_dwordx4 v[142:143], off
	s_waitcnt vmcnt(8)
	s_waitcnt lgkmcnt(0)
	s_barrier
	s_setprio 1
	s_waitcnt lgkmcnt(0)
	v_mfma_f32_16x16x32_bf16 v[62:65], v[148:151], v[214:217], v[62:65]
	v_mfma_f32_16x16x32_bf16 v[58:61], v[182:185], v[214:217], v[58:61]
	v_mfma_f32_16x16x32_bf16 v[46:49], v[148:151], v[222:225], v[46:49]
	v_mfma_f32_16x16x32_bf16 v[42:45], v[182:185], v[222:225], v[42:45]
	v_mfma_f32_16x16x32_bf16 v[30:33], v[148:151], v[230:233], v[30:33]
	v_mfma_f32_16x16x32_bf16 v[26:29], v[182:185], v[230:233], v[26:29]
	v_mfma_f32_16x16x32_bf16 v[14:17], v[148:151], v[238:241], v[14:17]
	v_mfma_f32_16x16x32_bf16 v[10:13], v[182:185], v[238:241], v[10:13]
	v_mfma_f32_16x16x32_bf16 v[62:65], v[152:155], v[218:221], v[62:65]
	v_mfma_f32_16x16x32_bf16 v[58:61], v[186:189], v[218:221], v[58:61]
	v_mfma_f32_16x16x32_bf16 v[46:49], v[152:155], v[226:229], v[46:49]
	v_mfma_f32_16x16x32_bf16 v[42:45], v[186:189], v[226:229], v[42:45]
	v_mfma_f32_16x16x32_bf16 v[30:33], v[152:155], v[234:237], v[30:33]
	v_mfma_f32_16x16x32_bf16 v[26:29], v[186:189], v[234:237], v[26:29]
	v_mfma_f32_16x16x32_bf16 v[14:17], v[152:155], v[242:245], v[14:17]
	v_mfma_f32_16x16x32_bf16 v[10:13], v[186:189], v[242:245], v[10:13]
	v_mfma_f32_16x16x32_bf16 v[54:57], v[190:193], v[214:217], v[54:57]
	v_mfma_f32_16x16x32_bf16 v[50:53], v[206:209], v[214:217], v[50:53]
	v_mfma_f32_16x16x32_bf16 v[38:41], v[190:193], v[222:225], v[38:41]
	v_mfma_f32_16x16x32_bf16 v[34:37], v[206:209], v[222:225], v[34:37]
	v_mfma_f32_16x16x32_bf16 v[22:25], v[190:193], v[230:233], v[22:25]
	v_mfma_f32_16x16x32_bf16 v[18:21], v[206:209], v[230:233], v[18:21]
	v_mfma_f32_16x16x32_bf16 v[6:9], v[190:193], v[238:241], v[6:9]
	v_mfma_f32_16x16x32_bf16 v[2:5], v[206:209], v[238:241], v[2:5]
	v_mfma_f32_16x16x32_bf16 v[54:57], v[202:205], v[218:221], v[54:57]
	v_mfma_f32_16x16x32_bf16 v[50:53], v[210:213], v[218:221], v[50:53]
	v_mfma_f32_16x16x32_bf16 v[38:41], v[202:205], v[226:229], v[38:41]
	v_mfma_f32_16x16x32_bf16 v[34:37], v[210:213], v[226:229], v[34:37]
	v_mfma_f32_16x16x32_bf16 v[22:25], v[202:205], v[234:237], v[22:25]
	v_mfma_f32_16x16x32_bf16 v[18:21], v[210:213], v[234:237], v[18:21]
	v_mfma_f32_16x16x32_bf16 v[6:9], v[202:205], v[242:245], v[6:9]
	v_mfma_f32_16x16x32_bf16 v[2:5], v[210:213], v[242:245], v[2:5]
	s_setprio 0
	s_barrier
	s_add_i32 s85, s85, 2
	s_add_u32 s76, s76, 0x100
	s_addc_u32 s84, s84, 0
	s_add_u32 s24, s24, 0x100
	s_addc_u32 s25, s25, 0
	s_cmp_gt_u32 s85, 13
	s_cbranch_scc0 .LBB0_955
	s_and_b64 vcc, exec, s[8:9]
	s_cbranch_vccz .LBB0_958
	s_barrier

.LBB0_1029:
	s_add_u32 s24, s22, 0x100
	s_addc_u32 s25, s23, 0
	s_add_i32 s12, 0, 0x10000
	s_cmp_eq_u32 s81, 40
	s_cselect_b32 s29, s7, s25
	s_cselect_b32 s28, s6, s24
	v_add_u32_e32 v0, s12, v150
	s_cselect_b32 s27, s21, s80
	s_cselect_b32 s26, s20, s76
	s_add_i32 s15, 0, 0x14000
	ds_read_b128 v[144:147], v0
	ds_read_b128 v[152:155], v0 offset:1024
	ds_read_b128 v[182:185], v0 offset:2048
	ds_read_b128 v[186:189], v0 offset:3072
	v_add_u32_e32 v0, s15, v150
	ds_read_b128 v[190:193], v0
	ds_read_b128 v[202:205], v0 offset:1024
	ds_read_b128 v[206:209], v0 offset:2048
	ds_read_b128 v[210:213], v0 offset:3072
	v_lshl_add_u64 v[148:149], s[22:23], 0, v[142:143]
	s_add_i32 m0, s34, 0xc000
	ds_read_b128 v[214:217], v151
	ds_read_b128 v[218:221], v151 offset:1024
	ds_read_b128 v[222:225], v151 offset:2048
	ds_read_b128 v[226:229], v151 offset:3072
	ds_read_b128 v[230:233], v151 offset:4096
	ds_read_b128 v[234:237], v151 offset:5120
	ds_read_b128 v[238:241], v151 offset:6144
	ds_read_b128 v[242:245], v151 offset:7168
	global_load_lds_dwordx4 v[148:149], off
	v_lshl_add_u64 v[148:149], s[22:23], 0, v[140:141]
	s_add_i32 m0, s34, 0xe000
	s_nop 0
	global_load_lds_dwordx4 v[148:149], off
	s_waitcnt vmcnt(8)
	s_waitcnt lgkmcnt(0)
	s_barrier
	s_setprio 1
	s_waitcnt lgkmcnt(0)
	v_mfma_f32_16x16x32_bf16 v[126:129], v[144:147], v[214:217], v[126:129]
	v_mfma_f32_16x16x32_bf16 v[122:125], v[182:185], v[214:217], v[122:125]
	v_mfma_f32_16x16x32_bf16 v[110:113], v[144:147], v[222:225], v[110:113]
	v_mfma_f32_16x16x32_bf16 v[106:109], v[182:185], v[222:225], v[106:109]
	v_mfma_f32_16x16x32_bf16 v[94:97], v[144:147], v[230:233], v[94:97]
	v_mfma_f32_16x16x32_bf16 v[90:93], v[182:185], v[230:233], v[90:93]
	v_mfma_f32_16x16x32_bf16 v[78:81], v[144:147], v[238:241], v[78:81]
	v_mfma_f32_16x16x32_bf16 v[74:77], v[182:185], v[238:241], v[74:77]
	v_mfma_f32_16x16x32_bf16 v[126:129], v[152:155], v[218:221], v[126:129]
	v_mfma_f32_16x16x32_bf16 v[122:125], v[186:189], v[218:221], v[122:125]
	v_mfma_f32_16x16x32_bf16 v[110:113], v[152:155], v[226:229], v[110:113]
	v_mfma_f32_16x16x32_bf16 v[106:109], v[186:189], v[226:229], v[106:109]
	v_mfma_f32_16x16x32_bf16 v[94:97], v[152:155], v[234:237], v[94:97]
	v_mfma_f32_16x16x32_bf16 v[90:93], v[186:189], v[234:237], v[90:93]
	v_mfma_f32_16x16x32_bf16 v[78:81], v[152:155], v[242:245], v[78:81]
	v_mfma_f32_16x16x32_bf16 v[74:77], v[186:189], v[242:245], v[74:77]
	v_mfma_f32_16x16x32_bf16 v[118:121], v[190:193], v[214:217], v[118:121]
	v_mfma_f32_16x16x32_bf16 v[114:117], v[206:209], v[214:217], v[114:117]
	v_mfma_f32_16x16x32_bf16 v[102:105], v[190:193], v[222:225], v[102:105]
	v_mfma_f32_16x16x32_bf16 v[98:101], v[206:209], v[222:225], v[98:101]
	v_mfma_f32_16x16x32_bf16 v[86:89], v[190:193], v[230:233], v[86:89]
	v_mfma_f32_16x16x32_bf16 v[82:85], v[206:209], v[230:233], v[82:85]
	v_mfma_f32_16x16x32_bf16 v[70:73], v[190:193], v[238:241], v[70:73]
	v_mfma_f32_16x16x32_bf16 v[66:69], v[206:209], v[238:241], v[66:69]
	v_mfma_f32_16x16x32_bf16 v[118:121], v[202:205], v[218:221], v[118:121]
	v_mfma_f32_16x16x32_bf16 v[114:117], v[210:213], v[218:221], v[114:117]
	v_mfma_f32_16x16x32_bf16 v[102:105], v[202:205], v[226:229], v[102:105]
	v_mfma_f32_16x16x32_bf16 v[98:101], v[210:213], v[226:229], v[98:101]
	v_mfma_f32_16x16x32_bf16 v[86:89], v[202:205], v[234:237], v[86:89]
	v_mfma_f32_16x16x32_bf16 v[82:85], v[210:213], v[234:237], v[82:85]
	v_mfma_f32_16x16x32_bf16 v[70:73], v[202:205], v[242:245], v[70:73]
	v_mfma_f32_16x16x32_bf16 v[66:69], v[210:213], v[242:245], v[66:69]
	s_setprio 0
	s_barrier
	s_add_i32 s12, s12, s31
	v_lshl_add_u64 v[148:149], s[26:27], 0, v[132:133]
	s_mov_b32 m0, s12
	ds_read_b128 v[214:217], v151 offset:16384
	ds_read_b128 v[218:221], v151 offset:17408
	ds_read_b128 v[222:225], v151 offset:18432
	ds_read_b128 v[226:229], v151 offset:19456
	ds_read_b128 v[230:233], v151 offset:20480
	ds_read_b128 v[234:237], v151 offset:21504
	ds_read_b128 v[238:241], v151 offset:22528
	ds_read_b128 v[242:245], v151 offset:23552
	global_load_lds_dwordx4 v[148:149], off
	s_add_i32 m0, s12, 0x2000
	s_add_u32 s12, s26, 0xb0000
	v_lshl_add_u64 v[156:157], s[26:27], 0, v[136:137]
	s_addc_u32 s13, s27, 0
	s_add_i32 s15, s15, s31
	global_load_lds_dwordx4 v[156:157], off
	v_lshl_add_u64 v[200:201], s[12:13], 0, v[132:133]
	s_mov_b32 m0, s15
	v_lshl_add_u64 v[246:247], s[28:29], 0, v[134:135]
	global_load_lds_dwordx4 v[200:201], off
	v_lshl_add_u64 v[200:201], s[12:13], 0, v[136:137]
	s_add_i32 m0, s15, 0x2000
	s_nop 0
	global_load_lds_dwordx4 v[200:201], off
	v_lshl_add_u64 v[200:201], s[28:29], 0, v[130:131]
	s_mov_b32 m0, s34
	s_nop 0
	global_load_lds_dwordx4 v[200:201], off
	s_mov_b32 m0, s35
	s_nop 0
	global_load_lds_dwordx4 v[246:247], off
	s_waitcnt vmcnt(8)
	s_waitcnt lgkmcnt(0)
	s_barrier
	s_setprio 1
	s_waitcnt lgkmcnt(0)
	v_mfma_f32_16x16x32_bf16 v[62:65], v[144:147], v[214:217], v[62:65]
	v_mfma_f32_16x16x32_bf16 v[58:61], v[182:185], v[214:217], v[58:61]
	v_mfma_f32_16x16x32_bf16 v[46:49], v[144:147], v[222:225], v[46:49]
	v_mfma_f32_16x16x32_bf16 v[42:45], v[182:185], v[222:225], v[42:45]
	v_mfma_f32_16x16x32_bf16 v[30:33], v[144:147], v[230:233], v[30:33]
	v_mfma_f32_16x16x32_bf16 v[26:29], v[182:185], v[230:233], v[26:29]
	v_mfma_f32_16x16x32_bf16 v[14:17], v[144:147], v[238:241], v[14:17]
	v_mfma_f32_16x16x32_bf16 v[10:13], v[182:185], v[238:241], v[10:13]
	v_mfma_f32_16x16x32_bf16 v[62:65], v[152:155], v[218:221], v[62:65]
	v_mfma_f32_16x16x32_bf16 v[58:61], v[186:189], v[218:221], v[58:61]
	v_mfma_f32_16x16x32_bf16 v[46:49], v[152:155], v[226:229], v[46:49]
	v_mfma_f32_16x16x32_bf16 v[42:45], v[186:189], v[226:229], v[42:45]
	v_mfma_f32_16x16x32_bf16 v[30:33], v[152:155], v[234:237], v[30:33]
	v_mfma_f32_16x16x32_bf16 v[26:29], v[186:189], v[234:237], v[26:29]
	v_mfma_f32_16x16x32_bf16 v[14:17], v[152:155], v[242:245], v[14:17]
	v_mfma_f32_16x16x32_bf16 v[10:13], v[186:189], v[242:245], v[10:13]
	v_mfma_f32_16x16x32_bf16 v[54:57], v[190:193], v[214:217], v[54:57]
	v_mfma_f32_16x16x32_bf16 v[50:53], v[206:209], v[214:217], v[50:53]
	v_mfma_f32_16x16x32_bf16 v[38:41], v[190:193], v[222:225], v[38:41]
	v_mfma_f32_16x16x32_bf16 v[34:37], v[206:209], v[222:225], v[34:37]
	v_mfma_f32_16x16x32_bf16 v[22:25], v[190:193], v[230:233], v[22:25]
	v_mfma_f32_16x16x32_bf16 v[18:21], v[206:209], v[230:233], v[18:21]
	v_mfma_f32_16x16x32_bf16 v[6:9], v[190:193], v[238:241], v[6:9]
	v_mfma_f32_16x16x32_bf16 v[2:5], v[206:209], v[238:241], v[2:5]
	v_mfma_f32_16x16x32_bf16 v[54:57], v[202:205], v[218:221], v[54:57]
	v_mfma_f32_16x16x32_bf16 v[50:53], v[210:213], v[218:221], v[50:53]
	v_mfma_f32_16x16x32_bf16 v[38:41], v[202:205], v[226:229], v[38:41]
	v_mfma_f32_16x16x32_bf16 v[34:37], v[210:213], v[226:229], v[34:37]
	v_mfma_f32_16x16x32_bf16 v[22:25], v[202:205], v[234:237], v[22:25]
	v_mfma_f32_16x16x32_bf16 v[18:21], v[210:213], v[234:237], v[18:21]
	v_mfma_f32_16x16x32_bf16 v[6:9], v[202:205], v[242:245], v[6:9]
	v_mfma_f32_16x16x32_bf16 v[2:5], v[210:213], v[242:245], v[2:5]
	s_setprio 0
	s_barrier
	s_add_i32 s15, 0, 0x18000
	v_add_u32_e32 v0, s15, v150
	s_add_i32 s22, 0, 0x1c000
	ds_read_b128 v[144:147], v0
	ds_read_b128 v[152:155], v0 offset:1024
	ds_read_b128 v[182:185], v0 offset:2048
	ds_read_b128 v[186:189], v0 offset:3072
	v_add_u32_e32 v0, s22, v150
	ds_read_b128 v[190:193], v0
	ds_read_b128 v[202:205], v0 offset:1024
	ds_read_b128 v[206:209], v0 offset:2048
	ds_read_b128 v[210:213], v0 offset:3072
	s_add_u32 s12, s28, 0xb0000
	s_addc_u32 s13, s29, 0
	s_mov_b32 m0, s42
	v_lshl_add_u64 v[248:249], s[12:13], 0, v[130:131]
	ds_read_b128 v[214:217], v151 offset:32768
	ds_read_b128 v[218:221], v151 offset:33792
	ds_read_b128 v[222:225], v151 offset:34816
	ds_read_b128 v[226:229], v151 offset:35840
	ds_read_b128 v[230:233], v151 offset:36864
	ds_read_b128 v[234:237], v151 offset:37888
	ds_read_b128 v[238:241], v151 offset:38912
	ds_read_b128 v[242:245], v151 offset:39936
	global_load_lds_dwordx4 v[248:249], off
	v_lshl_add_u64 v[248:249], s[12:13], 0, v[134:135]
	s_mov_b32 m0, s43
	s_nop 0
	global_load_lds_dwordx4 v[248:249], off
	s_waitcnt vmcnt(8)
	s_waitcnt lgkmcnt(0)
	s_barrier
	s_setprio 1
	s_waitcnt lgkmcnt(0)
	v_mfma_f32_16x16x32_bf16 v[126:129], v[144:147], v[214:217], v[126:129]
	v_mfma_f32_16x16x32_bf16 v[122:125], v[182:185], v[214:217], v[122:125]
	v_mfma_f32_16x16x32_bf16 v[110:113], v[144:147], v[222:225], v[110:113]
	v_mfma_f32_16x16x32_bf16 v[106:109], v[182:185], v[222:225], v[106:109]
	v_mfma_f32_16x16x32_bf16 v[94:97], v[144:147], v[230:233], v[94:97]
	v_mfma_f32_16x16x32_bf16 v[90:93], v[182:185], v[230:233], v[90:93]
	v_mfma_f32_16x16x32_bf16 v[78:81], v[144:147], v[238:241], v[78:81]
	v_mfma_f32_16x16x32_bf16 v[74:77], v[182:185], v[238:241], v[74:77]
	v_mfma_f32_16x16x32_bf16 v[126:129], v[152:155], v[218:221], v[126:129]
	v_mfma_f32_16x16x32_bf16 v[122:125], v[186:189], v[218:221], v[122:125]
	v_mfma_f32_16x16x32_bf16 v[110:113], v[152:155], v[226:229], v[110:113]
	v_mfma_f32_16x16x32_bf16 v[106:109], v[186:189], v[226:229], v[106:109]
	v_mfma_f32_16x16x32_bf16 v[94:97], v[152:155], v[234:237], v[94:97]
	v_mfma_f32_16x16x32_bf16 v[90:93], v[186:189], v[234:237], v[90:93]
	v_mfma_f32_16x16x32_bf16 v[78:81], v[152:155], v[242:245], v[78:81]
	v_mfma_f32_16x16x32_bf16 v[74:77], v[186:189], v[242:245], v[74:77]
	v_mfma_f32_16x16x32_bf16 v[118:121], v[190:193], v[214:217], v[118:121]
	v_mfma_f32_16x16x32_bf16 v[114:117], v[206:209], v[214:217], v[114:117]
	v_mfma_f32_16x16x32_bf16 v[102:105], v[190:193], v[222:225], v[102:105]
	v_mfma_f32_16x16x32_bf16 v[98:101], v[206:209], v[222:225], v[98:101]
	v_mfma_f32_16x16x32_bf16 v[86:89], v[190:193], v[230:233], v[86:89]
	v_mfma_f32_16x16x32_bf16 v[82:85], v[206:209], v[230:233], v[82:85]
	v_mfma_f32_16x16x32_bf16 v[70:73], v[190:193], v[238:241], v[70:73]
	v_mfma_f32_16x16x32_bf16 v[66:69], v[206:209], v[238:241], v[66:69]
	v_mfma_f32_16x16x32_bf16 v[118:121], v[202:205], v[218:221], v[118:121]
	v_mfma_f32_16x16x32_bf16 v[114:117], v[210:213], v[218:221], v[114:117]
	v_mfma_f32_16x16x32_bf16 v[102:105], v[202:205], v[226:229], v[102:105]
	v_mfma_f32_16x16x32_bf16 v[98:101], v[210:213], v[226:229], v[98:101]
	v_mfma_f32_16x16x32_bf16 v[86:89], v[202:205], v[234:237], v[86:89]
	v_mfma_f32_16x16x32_bf16 v[82:85], v[210:213], v[234:237], v[82:85]
	v_mfma_f32_16x16x32_bf16 v[70:73], v[202:205], v[242:245], v[70:73]
	v_mfma_f32_16x16x32_bf16 v[66:69], v[210:213], v[242:245], v[66:69]
	s_setprio 0
	s_barrier
	s_add_i32 s12, s15, s31
	v_lshl_add_u64 v[148:149], v[148:149], 0, s[94:95]
	s_mov_b32 m0, s12
	ds_read_b128 v[214:217], v151 offset:49152
	ds_read_b128 v[218:221], v151 offset:50176
	ds_read_b128 v[222:225], v151 offset:51200
	ds_read_b128 v[226:229], v151 offset:52224
	ds_read_b128 v[230:233], v151 offset:53248
	ds_read_b128 v[234:237], v151 offset:54272
	ds_read_b128 v[238:241], v151 offset:55296
	ds_read_b128 v[242:245], v151 offset:56320
	global_load_lds_dwordx4 v[148:149], off
	s_add_i32 m0, s12, 0x2000
	s_add_u32 s12, s26, 0xb0080
	v_lshl_add_u64 v[148:149], v[156:157], 0, s[94:95]
	s_addc_u32 s13, s27, 0
	s_add_i32 s15, s22, s31
	global_load_lds_dwordx4 v[148:149], off
	v_lshl_add_u64 v[148:149], s[12:13], 0, v[132:133]
	s_mov_b32 m0, s15
	s_nop 0
	global_load_lds_dwordx4 v[148:149], off
	v_lshl_add_u64 v[148:149], s[12:13], 0, v[136:137]
	s_add_i32 m0, s15, 0x2000
	s_nop 0
	global_load_lds_dwordx4 v[148:149], off
	v_lshl_add_u64 v[148:149], v[200:201], 0, s[94:95]
	s_mov_b32 m0, s46
	s_nop 0
	global_load_lds_dwordx4 v[148:149], off
	v_lshl_add_u64 v[148:149], v[246:247], 0, s[94:95]
	s_mov_b32 m0, s47
	s_nop 0
	global_load_lds_dwordx4 v[148:149], off
	s_waitcnt vmcnt(8)
	s_waitcnt lgkmcnt(0)
	s_barrier
	s_setprio 1
	s_waitcnt lgkmcnt(0)
	v_mfma_f32_16x16x32_bf16 v[62:65], v[144:147], v[214:217], v[62:65]
	v_mfma_f32_16x16x32_bf16 v[58:61], v[182:185], v[214:217], v[58:61]
	v_mfma_f32_16x16x32_bf16 v[46:49], v[144:147], v[222:225], v[46:49]
	v_mfma_f32_16x16x32_bf16 v[42:45], v[182:185], v[222:225], v[42:45]
	v_mfma_f32_16x16x32_bf16 v[30:33], v[144:147], v[230:233], v[30:33]
	v_mfma_f32_16x16x32_bf16 v[26:29], v[182:185], v[230:233], v[26:29]
	v_mfma_f32_16x16x32_bf16 v[14:17], v[144:147], v[238:241], v[14:17]
	v_mfma_f32_16x16x32_bf16 v[10:13], v[182:185], v[238:241], v[10:13]
	v_mfma_f32_16x16x32_bf16 v[62:65], v[152:155], v[218:221], v[62:65]
	v_mfma_f32_16x16x32_bf16 v[58:61], v[186:189], v[218:221], v[58:61]
	v_mfma_f32_16x16x32_bf16 v[46:49], v[152:155], v[226:229], v[46:49]
	v_mfma_f32_16x16x32_bf16 v[42:45], v[186:189], v[226:229], v[42:45]
	v_mfma_f32_16x16x32_bf16 v[30:33], v[152:155], v[234:237], v[30:33]
	v_mfma_f32_16x16x32_bf16 v[26:29], v[186:189], v[234:237], v[26:29]
	v_mfma_f32_16x16x32_bf16 v[14:17], v[152:155], v[242:245], v[14:17]
	v_mfma_f32_16x16x32_bf16 v[10:13], v[186:189], v[242:245], v[10:13]
	v_mfma_f32_16x16x32_bf16 v[54:57], v[190:193], v[214:217], v[54:57]
	v_mfma_f32_16x16x32_bf16 v[50:53], v[206:209], v[214:217], v[50:53]
	v_mfma_f32_16x16x32_bf16 v[38:41], v[190:193], v[222:225], v[38:41]
	v_mfma_f32_16x16x32_bf16 v[34:37], v[206:209], v[222:225], v[34:37]
	v_mfma_f32_16x16x32_bf16 v[22:25], v[190:193], v[230:233], v[22:25]
	v_mfma_f32_16x16x32_bf16 v[18:21], v[206:209], v[230:233], v[18:21]
	v_mfma_f32_16x16x32_bf16 v[6:9], v[190:193], v[238:241], v[6:9]
	v_mfma_f32_16x16x32_bf16 v[2:5], v[206:209], v[238:241], v[2:5]
	v_mfma_f32_16x16x32_bf16 v[54:57], v[202:205], v[218:221], v[54:57]
	v_mfma_f32_16x16x32_bf16 v[50:53], v[210:213], v[218:221], v[50:53]
	v_mfma_f32_16x16x32_bf16 v[38:41], v[202:205], v[226:229], v[38:41]
	v_mfma_f32_16x16x32_bf16 v[34:37], v[210:213], v[226:229], v[34:37]
	v_mfma_f32_16x16x32_bf16 v[22:25], v[202:205], v[234:237], v[22:25]
	v_mfma_f32_16x16x32_bf16 v[18:21], v[210:213], v[234:237], v[18:21]
	v_mfma_f32_16x16x32_bf16 v[6:9], v[202:205], v[242:245], v[6:9]
	v_mfma_f32_16x16x32_bf16 v[2:5], v[210:213], v[242:245], v[2:5]
	s_setprio 0
	s_barrier
	s_add_i32 s81, s81, 2
	s_add_u32 s76, s76, 0x100
	s_addc_u32 s80, s80, 0
	s_cmp_gt_u32 s81, 41
	s_mov_b64 s[22:23], s[24:25]
	s_cbranch_scc0 .LBB0_1029
	s_and_b64 vcc, exec, s[18:19]
	s_cbranch_vccz .LBB0_1032
	s_barrier
